# GEMM epilogue VALU trims: relu canonicalize removed, int64->f32 rstd chain 15->5 instrs, packed sum-of-squares, 64-bit acc zeroing, cvt writes exchange regs directly (on top of hoisted ss loads + full
# speedup vs baseline: 1.0167x; 1.0167x over previous
; template <class Epi, class Sched, bool ALIGN_EPI = false, bool SP2 = false>
; __device__ __forceinline__ void gemm_phase(PG8_LAS unsigned char* lds, const Gemm g, const Sched& S, const Epi& E) {
;     ...
;         const char* nA = has_next ? (const char*)g.A + (size_t)nxt.pm * tstep : cA; const char* nB = has_next ? (const char*)g.Bt + (size_t)nxt.pn * tstep : cB;
;         for (int t = 0; t < nt; t += 2) {
;             const bool last = (t == nt - 2);
;             const char* a1 = cA + (size_t)(t + 1) * kstep;
;             const char* a2 = last ? nA : cA + (size_t)(t + 2) * kstep; const char* b2 = last ? nB : cB + (size_t)(t + 2) * kstep;
;             const char* a3 = a2 + kstep; const char* b3 = b2 + kstep;
;     ...
; #pragma unroll
;         for (int a = 0; a < 2; ++a)
; #pragma unroll
;             for (int b = 0; b < 2; ++b)
; #pragma unroll
;                 for (int m = 0; m < 4; ++m)
; #pragma unroll
;                     for (int n = 0; n < 2; ++n) acc[a][b][m][n] = (f32x4){0.f, 0.f, 0.f, 0.f};
;         cur = nxt; cA = nA; cB = nB; ++ui;
.LBB0_247:
	s_add_u32 s40, s40, 0x80
	s_addc_u32 s41, s41, 0
	s_add_u32 s92, s66, 0x100
	s_addc_u32 s95, s67, 0
	s_mov_b32 s2, 0
	s_waitcnt lgkmcnt(0)
	v_mov_b64_e32 v[0:1], 0
	v_mov_b64_e32 v[2:3], 0
	v_mov_b64_e32 v[4:5], 0
	v_mov_b64_e32 v[6:7], 0
	v_mov_b64_e32 v[8:9], 0
	v_mov_b64_e32 v[10:11], 0
	v_mov_b64_e32 v[12:13], 0
	v_mov_b64_e32 v[14:15], 0
	v_mov_b64_e32 v[16:17], 0
	v_mov_b64_e32 v[18:19], 0
	v_mov_b64_e32 v[20:21], 0
	v_mov_b64_e32 v[22:23], 0
	v_mov_b64_e32 v[24:25], 0
	v_mov_b64_e32 v[26:27], 0
	v_mov_b64_e32 v[28:29], 0
	v_mov_b64_e32 v[30:31], 0
	v_mov_b64_e32 v[32:33], 0
	v_mov_b64_e32 v[34:35], 0
	v_mov_b64_e32 v[36:37], 0
	v_mov_b64_e32 v[38:39], 0
	v_mov_b64_e32 v[40:41], 0
	v_mov_b64_e32 v[42:43], 0
	v_mov_b64_e32 v[44:45], 0
	v_mov_b64_e32 v[46:47], 0
	v_mov_b64_e32 v[48:49], 0
	v_mov_b64_e32 v[50:51], 0
	v_mov_b64_e32 v[52:53], 0
	v_mov_b64_e32 v[54:55], 0
	v_mov_b64_e32 v[56:57], 0
	v_mov_b64_e32 v[58:59], 0
	v_mov_b64_e32 v[60:61], 0
	v_mov_b64_e32 v[62:63], 0
	v_mov_b64_e32 v[64:65], 0
	v_mov_b64_e32 v[66:67], 0
	v_mov_b64_e32 v[68:69], 0
	v_mov_b64_e32 v[70:71], 0
	v_mov_b64_e32 v[72:73], 0
	v_mov_b64_e32 v[74:75], 0
	v_mov_b64_e32 v[76:77], 0
	v_mov_b64_e32 v[78:79], 0
	v_mov_b64_e32 v[88:89], 0
	v_mov_b64_e32 v[90:91], 0
	v_mov_b64_e32 v[92:93], 0
	v_mov_b64_e32 v[94:95], 0
	v_mov_b64_e32 v[96:97], 0
	v_mov_b64_e32 v[98:99], 0
	v_mov_b64_e32 v[104:105], 0
	v_mov_b64_e32 v[106:107], 0
	v_mov_b64_e32 v[114:115], 0
	v_mov_b64_e32 v[116:117], 0
	v_mov_b64_e32 v[118:119], 0
	v_mov_b64_e32 v[120:121], 0
	v_mov_b64_e32 v[126:127], 0
	v_mov_b64_e32 v[128:129], 0
	v_mov_b64_e32 v[130:131], 0
	v_mov_b64_e32 v[132:133], 0
	v_mov_b64_e32 v[138:139], 0
	v_mov_b64_e32 v[140:141], 0
	v_mov_b64_e32 v[142:143], 0
	v_mov_b64_e32 v[144:145], 0
	v_mov_b64_e32 v[150:151], 0
	v_mov_b64_e32 v[152:153], 0
	v_mov_b64_e32 v[154:155], 0
	v_mov_b64_e32 v[156:157], 0

; template <class Epi, class Sched, bool ALIGN_EPI = false, bool SP2 = false>
; __device__ __forceinline__ void gemm_phase(PG8_LAS unsigned char* lds, const Gemm g, const Sched& S, const Epi& E) {
;     ...
;         const bool has_next = S.next(ui + 1, nxt);
;         const char* nA = has_next ? (const char*)g.A + (size_t)nxt.pm * tstep : cA; const char* nB = has_next ? (const char*)g.Bt + (size_t)nxt.pn * tstep : cB;
;         for (int t = 0; t < nt; t += 2) {
;             const bool last = (t == nt - 2);
;             const char* a1 = cA + (size_t)(t + 1) * kstep;
;             const char* a2 = last ? nA : cA + (size_t)(t + 2) * kstep; const char* b2 = last ? nB : cB + (size_t)(t + 2) * kstep;
;             const char* a3 = a2 + kstep; const char* b3 = b2 + kstep;
;     ...
; #pragma unroll
;         for (int a = 0; a < 2; ++a)
; #pragma unroll
;             for (int b = 0; b < 2; ++b)
; #pragma unroll
;                 for (int m = 0; m < 4; ++m)
; #pragma unroll
;                     for (int n = 0; n < 2; ++n) acc[a][b][m][n] = (f32x4){0.f, 0.f, 0.f, 0.f};
;         cur = nxt; cA = nA; cB = nB; ++ui;
.LBB0_353:
	s_ashr_i32 s71, s70, 31
	s_lshl_b64 s[72:73], s[70:71], 19
	s_add_u32 s72, s52, s72
	s_addc_u32 s73, s53, s73
	s_and_b64 s[74:75], s[38:39], exec
	s_cselect_b32 s1, s73, s43
	s_cselect_b32 s34, s72, s42
	s_ashr_i32 s69, s68, 31
	s_lshl_b64 s[74:75], s[68:69], 19
	s_add_u32 s74, s44, s74
	s_addc_u32 s75, s45, s75
	s_and_b64 s[88:89], s[38:39], exec
	s_cselect_b32 s41, s75, s77
	s_cselect_b32 s69, s74, s76
	s_add_u32 s42, s42, 0x40080
	s_addc_u32 s43, s43, 0
	s_add_u32 s71, s76, 0x100
	s_addc_u32 s78, s77, 0
	s_mov_b32 s88, -2
	v_mov_b64_e32 v[0:1], 0
	v_mov_b64_e32 v[2:3], 0
	v_mov_b64_e32 v[4:5], 0
	v_mov_b64_e32 v[6:7], 0
	v_mov_b64_e32 v[8:9], 0
	v_mov_b64_e32 v[10:11], 0
	v_mov_b64_e32 v[12:13], 0
	v_mov_b64_e32 v[14:15], 0
	v_mov_b64_e32 v[16:17], 0
	v_mov_b64_e32 v[18:19], 0
	v_mov_b64_e32 v[20:21], 0
	v_mov_b64_e32 v[22:23], 0
	v_mov_b64_e32 v[24:25], 0
	v_mov_b64_e32 v[26:27], 0
	v_mov_b64_e32 v[28:29], 0
	v_mov_b64_e32 v[30:31], 0
	v_mov_b64_e32 v[32:33], 0
	v_mov_b64_e32 v[34:35], 0
	v_mov_b64_e32 v[36:37], 0
	v_mov_b64_e32 v[38:39], 0
	v_mov_b64_e32 v[40:41], 0
	v_mov_b64_e32 v[42:43], 0
	v_mov_b64_e32 v[44:45], 0
	v_mov_b64_e32 v[46:47], 0
	v_mov_b64_e32 v[48:49], 0
	v_mov_b64_e32 v[50:51], 0
	v_mov_b64_e32 v[52:53], 0
	v_mov_b64_e32 v[54:55], 0
	v_mov_b64_e32 v[56:57], 0
	v_mov_b64_e32 v[58:59], 0
	v_mov_b64_e32 v[60:61], 0
	v_mov_b64_e32 v[62:63], 0
	v_mov_b64_e32 v[64:65], 0
	v_mov_b64_e32 v[66:67], 0
	v_mov_b64_e32 v[68:69], 0
	v_mov_b64_e32 v[70:71], 0
	v_mov_b64_e32 v[72:73], 0
	v_mov_b64_e32 v[74:75], 0
	v_mov_b64_e32 v[76:77], 0
	v_mov_b64_e32 v[78:79], 0
	v_mov_b64_e32 v[96:97], 0
	v_mov_b64_e32 v[98:99], 0
	v_mov_b64_e32 v[100:101], 0
	v_mov_b64_e32 v[102:103], 0
	v_mov_b64_e32 v[104:105], 0
	v_mov_b64_e32 v[106:107], 0
	v_mov_b64_e32 v[108:109], 0
	v_mov_b64_e32 v[110:111], 0
	v_mov_b64_e32 v[114:115], 0
	v_mov_b64_e32 v[116:117], 0
	v_mov_b64_e32 v[118:119], 0
	v_mov_b64_e32 v[120:121], 0
	v_mov_b64_e32 v[122:123], 0
	v_mov_b64_e32 v[124:125], 0
	v_mov_b64_e32 v[126:127], 0
	v_mov_b64_e32 v[128:129], 0
	v_mov_b64_e32 v[130:131], 0
	v_mov_b64_e32 v[132:133], 0
	v_mov_b64_e32 v[134:135], 0
	v_mov_b64_e32 v[136:137], 0
	v_mov_b64_e32 v[138:139], 0
	v_mov_b64_e32 v[140:141], 0
	v_mov_b64_e32 v[142:143], 0
	v_mov_b64_e32 v[144:145], 0

;     __device__ __forceinline__ void operator()(const f32x4 (&acc)[2][2][4][2], const Unit& u, int wr, int wc, int fr, int fq) const {
;     ...
;                 const int r = row0 + ai * HALF + m * 16;
;                 const float rs = __builtin_amdgcn_rsqf((float)ss[r] * (1.0f / 1048576.0f) * (1.0f / 1024.0f) + EPS);
;                 bf16_t* rowp = O + (size_t)r * ldc + colt + wc * 32 + 8 * fq;
; #pragma unroll
;                 for (int bj = 0; bj < 2; ++bj) { f32x4 v0 = acc[ai][bj][m][0] * rs, v1 = acc[ai][bj][m][1] * rs;
;                     if (mode == 2) {
; #pragma unroll
;                         for (int e = 0; e < 4; ++e) { float a = fmaxf(v0[e], 0.f), b = fmaxf(v1[e], 0.f); v0[e] = a * a; v1[e] = b * b; } }
.LBB0_360:
	v_lshl_add_u64 v[80:81], v[160:161], 3, s[48:49]
	s_and_b64 vcc, exec, s[50:51]
	s_waitcnt vmcnt(0)
	s_nop 1
	v_cvt_f32_u32_e32 v83, v193
	v_cvt_f32_u32_e32 v82, v192
	v_fmamk_f32 v82, v83, 0x4f800000, v82
	v_fmamk_f32 v82, v82, 0x30800000, v229
	v_rsq_f32_e32 v82, v82
	s_nop 0
	v_pk_mul_f32 v[86:87], v[144:145], v[82:83] op_sel_hi:[1,0]
	v_pk_mul_f32 v[90:91], v[142:143], v[82:83] op_sel_hi:[1,0]
	v_pk_mul_f32 v[88:89], v[140:141], v[82:83] op_sel_hi:[1,0]
	v_pk_mul_f32 v[92:93], v[138:139], v[82:83] op_sel_hi:[1,0]
	s_cbranch_vccz .LBB0_362
	v_max_f32_e32 v84, 0, v90
	v_max_f32_e32 v92, 0, v92
	v_max_f32_e32 v85, 0, v91
	v_max_f32_e32 v93, 0, v93
	v_max_f32_e32 v86, 0, v86
	v_max_f32_e32 v88, 0, v88
	v_max_f32_e32 v87, 0, v87
	v_max_f32_e32 v89, 0, v89
	v_pk_mul_f32 v[90:91], v[84:85], v[84:85]
	v_pk_mul_f32 v[86:87], v[86:87], v[86:87]
	v_pk_mul_f32 v[92:93], v[92:93], v[92:93]
	v_pk_mul_f32 v[88:89], v[88:89], v[88:89]

; __device__ __forceinline__ unsigned cvt_pk_bf16(float lo, float hi) { unsigned r; asm volatile("v_cvt_pk_bf16_f32 %0, %1, %2" : "=v"(r) : "v"(lo), "v"(hi)); return r; }
;     __device__ __forceinline__ void operator()(const f32x4 (&acc)[2][2][4][2], const Unit& u, int wr, int wc, int fr, int fq) const {
;     ...
;                 bf16_t* rowp = O + (size_t)r * ldc + colt + wc * 32 + 8 * fq;
; #pragma unroll
;                 for (int bj = 0; bj < 2; ++bj) { f32x4 v0 = acc[ai][bj][m][0] * rs, v1 = acc[ai][bj][m][1] * rs;
;                     if (mode == 2) {
; #pragma unroll
;                         for (int e = 0; e < 4; ++e) { float a = fmaxf(v0[e], 0.f), b = fmaxf(v1[e], 0.f); v0[e] = a * a; v1[e] = b * b; } }
;                     if (mode == 1 && colt >= 2048) {
; #pragma unroll
;                         for (int e = 0; e < 4; ++e) { v0[e] = __builtin_amdgcn_rcpf(1.0f + __builtin_amdgcn_exp2f(-1.4426950408889634f * v0[e])); v1[e] = __builtin_amdgcn_rcpf(1.0f + __builtin_amdgcn_exp2f(-1.4426950408889634f * v1[e])); } }
;                     u32x4 w; w.x = cvt_pk_bf16(v0[0], v0[1]); w.y = cvt_pk_bf16(v0[2], v0[3]); w.z = cvt_pk_bf16(v1[0], v1[1]); w.w = cvt_pk_bf16(v1[2], v1[3]);
;                     *(u32x4*)(rowp + bj * HALF) = w; }
.LBB0_364:
	v_mad_i64_i32 v[84:85], s[42:43], s54, v160, 0
	s_ashr_i32 s77, s76, 31
	v_lshl_add_u64 v[84:85], v[84:85], 1, s[28:29]
	v_lshl_add_u64 v[84:85], s[76:77], 1, v[84:85]
	s_lshl_b32 s34, s83, 1
	v_lshl_add_u64 v[84:85], v[84:85], 0, s[34:35]
	v_lshlrev_b32_e32 v112, 1, v154
	v_lshl_add_u64 v[84:85], v[84:85], 0, v[112:113]
	v_cvt_pk_bf16_f32 v90, v90, v91
	v_cvt_pk_bf16_f32 v91, v86, v87
	v_cvt_pk_bf16_f32 v92, v92, v93
	v_mov_b32_e32 v83, v82
	v_cvt_pk_bf16_f32 v93, v88, v89
	global_store_dwordx4 v[84:85], v[90:93], off
	v_mov_b32_e32 v88, v82
	v_mov_b32_e32 v89, v82
	v_cndmask_b32_e64 v92, 0, 1, s[50:51]
	v_pk_mul_f32 v[86:87], v[136:137], v[88:89]
	v_pk_mul_f32 v[90:91], v[134:135], v[82:83]
	v_pk_mul_f32 v[88:89], v[132:133], v[88:89]
	v_cmp_ne_u32_e64 s[42:43], 1, v92
	s_andn2_b64 vcc, exec, s[50:51]
	v_pk_mul_f32 v[82:83], v[130:131], v[82:83]
	s_cbranch_vccnz .LBB0_366
	v_max_f32_e32 v90, 0, v90
	v_max_f32_e32 v82, 0, v82
	v_max_f32_e32 v91, 0, v91
	v_max_f32_e32 v83, 0, v83
	v_max_f32_e32 v86, 0, v86
	v_max_f32_e32 v88, 0, v88
	v_max_f32_e32 v87, 0, v87
	v_max_f32_e32 v89, 0, v89
	v_pk_mul_f32 v[90:91], v[90:91], v[90:91]
	v_pk_mul_f32 v[86:87], v[86:87], v[86:87]
	v_pk_mul_f32 v[82:83], v[82:83], v[82:83]
	v_pk_mul_f32 v[88:89], v[88:89], v[88:89]

; __device__ __forceinline__ unsigned cvt_pk_bf16(float lo, float hi) { unsigned r; asm volatile("v_cvt_pk_bf16_f32 %0, %1, %2" : "=v"(r) : "v"(lo), "v"(hi)); return r; }
;     __device__ __forceinline__ void operator()(const f32x4 (&acc)[2][2][4][2], const Unit& u, int wr, int wc, int fr, int fq) const {
;     ...
;                 const int r = row0 + ai * HALF + m * 16;
;                 const float rs = __builtin_amdgcn_rsqf((float)ss[r] * (1.0f / 1048576.0f) * (1.0f / 1024.0f) + EPS);
;                 bf16_t* rowp = O + (size_t)r * ldc + colt + wc * 32 + 8 * fq;
; #pragma unroll
;                 for (int bj = 0; bj < 2; ++bj) { f32x4 v0 = acc[ai][bj][m][0] * rs, v1 = acc[ai][bj][m][1] * rs;
;                     if (mode == 2) {
; #pragma unroll
;                         for (int e = 0; e < 4; ++e) { float a = fmaxf(v0[e], 0.f), b = fmaxf(v1[e], 0.f); v0[e] = a * a; v1[e] = b * b; } }
;                     if (mode == 1 && colt >= 2048) {
; #pragma unroll
;                         for (int e = 0; e < 4; ++e) { v0[e] = __builtin_amdgcn_rcpf(1.0f + __builtin_amdgcn_exp2f(-1.4426950408889634f * v0[e])); v1[e] = __builtin_amdgcn_rcpf(1.0f + __builtin_amdgcn_exp2f(-1.4426950408889634f * v1[e])); } }
;                     u32x4 w; w.x = cvt_pk_bf16(v0[0], v0[1]); w.y = cvt_pk_bf16(v0[2], v0[3]); w.z = cvt_pk_bf16(v1[0], v1[1]); w.w = cvt_pk_bf16(v1[2], v1[3]);
;                     *(u32x4*)(rowp + bj * HALF) = w; }
.LBB0_368:
	v_cvt_pk_bf16_f32 v90, v90, v91
	v_cvt_pk_bf16_f32 v91, v86, v87
	v_cvt_pk_bf16_f32 v92, v82, v83
	v_cvt_pk_bf16_f32 v93, v88, v89
	global_store_dwordx4 v[84:85], v[90:93], off offset:256
	s_and_b64 vcc, exec, s[42:43]
	s_nop 1
	v_cvt_f32_u32_e32 v83, v195
	v_cvt_f32_u32_e32 v82, v194
	v_fmamk_f32 v82, v83, 0x4f800000, v82
	v_fmamk_f32 v82, v82, 0x30800000, v229
	v_rsq_f32_e32 v82, v82
	s_nop 0
	v_pk_mul_f32 v[86:87], v[128:129], v[82:83] op_sel_hi:[1,0]
	v_pk_mul_f32 v[90:91], v[126:127], v[82:83] op_sel_hi:[1,0]
	v_pk_mul_f32 v[88:89], v[124:125], v[82:83] op_sel_hi:[1,0]
	v_pk_mul_f32 v[92:93], v[122:123], v[82:83] op_sel_hi:[1,0]
	s_cbranch_vccnz .LBB0_370
	v_max_f32_e32 v84, 0, v90
	v_max_f32_e32 v92, 0, v92
	v_max_f32_e32 v85, 0, v91
	v_max_f32_e32 v93, 0, v93
	v_max_f32_e32 v86, 0, v86
	v_max_f32_e32 v88, 0, v88
	v_max_f32_e32 v87, 0, v87
	v_max_f32_e32 v89, 0, v89
	v_pk_mul_f32 v[90:91], v[84:85], v[84:85]
	v_pk_mul_f32 v[86:87], v[86:87], v[86:87]
	v_pk_mul_f32 v[92:93], v[92:93], v[92:93]
	v_pk_mul_f32 v[88:89], v[88:89], v[88:89]

; __device__ __forceinline__ unsigned cvt_pk_bf16(float lo, float hi) { unsigned r; asm volatile("v_cvt_pk_bf16_f32 %0, %1, %2" : "=v"(r) : "v"(lo), "v"(hi)); return r; }
;     __device__ __forceinline__ void operator()(const f32x4 (&acc)[2][2][4][2], const Unit& u, int wr, int wc, int fr, int fq) const {
;     ...
;                 bf16_t* rowp = O + (size_t)r * ldc + colt + wc * 32 + 8 * fq;
; #pragma unroll
;                 for (int bj = 0; bj < 2; ++bj) { f32x4 v0 = acc[ai][bj][m][0] * rs, v1 = acc[ai][bj][m][1] * rs;
;                     if (mode == 2) {
; #pragma unroll
;                         for (int e = 0; e < 4; ++e) { float a = fmaxf(v0[e], 0.f), b = fmaxf(v1[e], 0.f); v0[e] = a * a; v1[e] = b * b; } }
;                     if (mode == 1 && colt >= 2048) {
; #pragma unroll
;                         for (int e = 0; e < 4; ++e) { v0[e] = __builtin_amdgcn_rcpf(1.0f + __builtin_amdgcn_exp2f(-1.4426950408889634f * v0[e])); v1[e] = __builtin_amdgcn_rcpf(1.0f + __builtin_amdgcn_exp2f(-1.4426950408889634f * v1[e])); } }
;                     u32x4 w; w.x = cvt_pk_bf16(v0[0], v0[1]); w.y = cvt_pk_bf16(v0[2], v0[3]); w.z = cvt_pk_bf16(v1[0], v1[1]); w.w = cvt_pk_bf16(v1[2], v1[3]);
;                     *(u32x4*)(rowp + bj * HALF) = w; }
.LBB0_372:
	v_or_b32_e32 v84, 16, v160
	v_mad_i64_i32 v[84:85], s[88:89], s54, v84, 0
	v_lshl_add_u64 v[84:85], v[84:85], 1, s[28:29]
	v_lshl_add_u64 v[84:85], s[76:77], 1, v[84:85]
	v_lshl_add_u64 v[84:85], v[84:85], 0, s[34:35]
	v_mov_b32_e32 v83, v82
	v_lshl_add_u64 v[84:85], v[84:85], 0, v[112:113]
	v_cvt_pk_bf16_f32 v90, v90, v91
	v_cvt_pk_bf16_f32 v91, v86, v87
	v_cvt_pk_bf16_f32 v92, v92, v93
	v_cvt_pk_bf16_f32 v93, v88, v89
	v_mov_b32_e32 v88, v82
	v_mov_b32_e32 v89, v82
	global_store_dwordx4 v[84:85], v[90:93], off
	v_pk_mul_f32 v[86:87], v[120:121], v[88:89]
	v_pk_mul_f32 v[88:89], v[116:117], v[88:89]
	v_pk_mul_f32 v[90:91], v[118:119], v[82:83]
	s_and_b64 vcc, exec, s[42:43]
	v_pk_mul_f32 v[82:83], v[114:115], v[82:83]
	s_cbranch_vccnz .LBB0_374
	v_max_f32_e32 v90, 0, v90
	v_max_f32_e32 v82, 0, v82
	v_max_f32_e32 v91, 0, v91
	v_max_f32_e32 v83, 0, v83
	v_max_f32_e32 v86, 0, v86
	v_max_f32_e32 v88, 0, v88
	v_max_f32_e32 v87, 0, v87
	v_max_f32_e32 v89, 0, v89
	v_pk_mul_f32 v[90:91], v[90:91], v[90:91]
	v_pk_mul_f32 v[86:87], v[86:87], v[86:87]
	v_pk_mul_f32 v[82:83], v[82:83], v[82:83]
	v_pk_mul_f32 v[88:89], v[88:89], v[88:89]

; __device__ __forceinline__ unsigned cvt_pk_bf16(float lo, float hi) { unsigned r; asm volatile("v_cvt_pk_bf16_f32 %0, %1, %2" : "=v"(r) : "v"(lo), "v"(hi)); return r; }
;     __device__ __forceinline__ void operator()(const f32x4 (&acc)[2][2][4][2], const Unit& u, int wr, int wc, int fr, int fq) const {
;     ...
;                 const int r = row0 + ai * HALF + m * 16;
;                 const float rs = __builtin_amdgcn_rsqf((float)ss[r] * (1.0f / 1048576.0f) * (1.0f / 1024.0f) + EPS);
;                 bf16_t* rowp = O + (size_t)r * ldc + colt + wc * 32 + 8 * fq;
; #pragma unroll
;                 for (int bj = 0; bj < 2; ++bj) { f32x4 v0 = acc[ai][bj][m][0] * rs, v1 = acc[ai][bj][m][1] * rs;
;                     if (mode == 2) {
; #pragma unroll
;                         for (int e = 0; e < 4; ++e) { float a = fmaxf(v0[e], 0.f), b = fmaxf(v1[e], 0.f); v0[e] = a * a; v1[e] = b * b; } }
;                     if (mode == 1 && colt >= 2048) {
; #pragma unroll
;                         for (int e = 0; e < 4; ++e) { v0[e] = __builtin_amdgcn_rcpf(1.0f + __builtin_amdgcn_exp2f(-1.4426950408889634f * v0[e])); v1[e] = __builtin_amdgcn_rcpf(1.0f + __builtin_amdgcn_exp2f(-1.4426950408889634f * v1[e])); } }
;                     u32x4 w; w.x = cvt_pk_bf16(v0[0], v0[1]); w.y = cvt_pk_bf16(v0[2], v0[3]); w.z = cvt_pk_bf16(v1[0], v1[1]); w.w = cvt_pk_bf16(v1[2], v1[3]);
;                     *(u32x4*)(rowp + bj * HALF) = w; }
.LBB0_376:
	v_cvt_pk_bf16_f32 v90, v90, v91
	v_cvt_pk_bf16_f32 v91, v86, v87
	v_cvt_pk_bf16_f32 v92, v82, v83
	v_cvt_pk_bf16_f32 v93, v88, v89
	global_store_dwordx4 v[84:85], v[90:93], off offset:256
	s_and_b64 vcc, exec, s[42:43]
	s_nop 1
	v_cvt_f32_u32_e32 v83, v197
	v_cvt_f32_u32_e32 v82, v196
	v_fmamk_f32 v82, v83, 0x4f800000, v82
	v_fmamk_f32 v82, v82, 0x30800000, v229
	v_rsq_f32_e32 v82, v82
	s_nop 0
	v_pk_mul_f32 v[86:87], v[110:111], v[82:83] op_sel_hi:[1,0]
	v_pk_mul_f32 v[90:91], v[108:109], v[82:83] op_sel_hi:[1,0]
	v_pk_mul_f32 v[88:89], v[106:107], v[82:83] op_sel_hi:[1,0]
	v_pk_mul_f32 v[92:93], v[104:105], v[82:83] op_sel_hi:[1,0]
	s_cbranch_vccnz .LBB0_378
	v_max_f32_e32 v84, 0, v90
	v_max_f32_e32 v92, 0, v92
	v_max_f32_e32 v85, 0, v91
	v_max_f32_e32 v93, 0, v93
	v_max_f32_e32 v86, 0, v86
	v_max_f32_e32 v88, 0, v88
	v_max_f32_e32 v87, 0, v87
	v_max_f32_e32 v89, 0, v89
	v_pk_mul_f32 v[90:91], v[84:85], v[84:85]
	v_pk_mul_f32 v[86:87], v[86:87], v[86:87]
	v_pk_mul_f32 v[92:93], v[92:93], v[92:93]
	v_pk_mul_f32 v[88:89], v[88:89], v[88:89]

; __device__ __forceinline__ unsigned cvt_pk_bf16(float lo, float hi) { unsigned r; asm volatile("v_cvt_pk_bf16_f32 %0, %1, %2" : "=v"(r) : "v"(lo), "v"(hi)); return r; }
;     __device__ __forceinline__ void operator()(const f32x4 (&acc)[2][2][4][2], const Unit& u, int wr, int wc, int fr, int fq) const {
;     ...
;                 bf16_t* rowp = O + (size_t)r * ldc + colt + wc * 32 + 8 * fq;
; #pragma unroll
;                 for (int bj = 0; bj < 2; ++bj) { f32x4 v0 = acc[ai][bj][m][0] * rs, v1 = acc[ai][bj][m][1] * rs;
;                     if (mode == 2) {
; #pragma unroll
;                         for (int e = 0; e < 4; ++e) { float a = fmaxf(v0[e], 0.f), b = fmaxf(v1[e], 0.f); v0[e] = a * a; v1[e] = b * b; } }
;                     if (mode == 1 && colt >= 2048) {
; #pragma unroll
;                         for (int e = 0; e < 4; ++e) { v0[e] = __builtin_amdgcn_rcpf(1.0f + __builtin_amdgcn_exp2f(-1.4426950408889634f * v0[e])); v1[e] = __builtin_amdgcn_rcpf(1.0f + __builtin_amdgcn_exp2f(-1.4426950408889634f * v1[e])); } }
;                     u32x4 w; w.x = cvt_pk_bf16(v0[0], v0[1]); w.y = cvt_pk_bf16(v0[2], v0[3]); w.z = cvt_pk_bf16(v1[0], v1[1]); w.w = cvt_pk_bf16(v1[2], v1[3]);
;                     *(u32x4*)(rowp + bj * HALF) = w; }
.LBB0_380:
	v_or_b32_e32 v84, 32, v160
	v_mad_i64_i32 v[84:85], s[88:89], s54, v84, 0
	v_lshl_add_u64 v[84:85], v[84:85], 1, s[28:29]
	v_lshl_add_u64 v[84:85], s[76:77], 1, v[84:85]
	v_lshl_add_u64 v[84:85], v[84:85], 0, s[34:35]
	v_mov_b32_e32 v83, v82
	v_lshl_add_u64 v[84:85], v[84:85], 0, v[112:113]
	v_cvt_pk_bf16_f32 v90, v90, v91
	v_cvt_pk_bf16_f32 v91, v86, v87
	v_cvt_pk_bf16_f32 v92, v92, v93
	v_cvt_pk_bf16_f32 v93, v88, v89
	v_mov_b32_e32 v88, v82
	v_mov_b32_e32 v89, v82
	global_store_dwordx4 v[84:85], v[90:93], off
	v_pk_mul_f32 v[86:87], v[102:103], v[88:89]
	v_pk_mul_f32 v[88:89], v[98:99], v[88:89]
	v_pk_mul_f32 v[90:91], v[100:101], v[82:83]
	s_and_b64 vcc, exec, s[42:43]
	v_pk_mul_f32 v[82:83], v[96:97], v[82:83]
	s_cbranch_vccnz .LBB0_382
	v_max_f32_e32 v90, 0, v90
	v_max_f32_e32 v82, 0, v82
	v_max_f32_e32 v91, 0, v91
	v_max_f32_e32 v83, 0, v83
	v_max_f32_e32 v86, 0, v86
	v_max_f32_e32 v88, 0, v88
	v_max_f32_e32 v87, 0, v87
	v_max_f32_e32 v89, 0, v89
	v_pk_mul_f32 v[90:91], v[90:91], v[90:91]
	v_pk_mul_f32 v[86:87], v[86:87], v[86:87]
	v_pk_mul_f32 v[82:83], v[82:83], v[82:83]
	v_pk_mul_f32 v[88:89], v[88:89], v[88:89]

; __device__ __forceinline__ unsigned cvt_pk_bf16(float lo, float hi) { unsigned r; asm volatile("v_cvt_pk_bf16_f32 %0, %1, %2" : "=v"(r) : "v"(lo), "v"(hi)); return r; }
;     __device__ __forceinline__ void operator()(const f32x4 (&acc)[2][2][4][2], const Unit& u, int wr, int wc, int fr, int fq) const {
;     ...
;                 const int r = row0 + ai * HALF + m * 16;
;                 const float rs = __builtin_amdgcn_rsqf((float)ss[r] * (1.0f / 1048576.0f) * (1.0f / 1024.0f) + EPS);
;                 bf16_t* rowp = O + (size_t)r * ldc + colt + wc * 32 + 8 * fq;
; #pragma unroll
;                 for (int bj = 0; bj < 2; ++bj) { f32x4 v0 = acc[ai][bj][m][0] * rs, v1 = acc[ai][bj][m][1] * rs;
;                     if (mode == 2) {
; #pragma unroll
;                         for (int e = 0; e < 4; ++e) { float a = fmaxf(v0[e], 0.f), b = fmaxf(v1[e], 0.f); v0[e] = a * a; v1[e] = b * b; } }
;                     if (mode == 1 && colt >= 2048) {
; #pragma unroll
;                         for (int e = 0; e < 4; ++e) { v0[e] = __builtin_amdgcn_rcpf(1.0f + __builtin_amdgcn_exp2f(-1.4426950408889634f * v0[e])); v1[e] = __builtin_amdgcn_rcpf(1.0f + __builtin_amdgcn_exp2f(-1.4426950408889634f * v1[e])); } }
;                     u32x4 w; w.x = cvt_pk_bf16(v0[0], v0[1]); w.y = cvt_pk_bf16(v0[2], v0[3]); w.z = cvt_pk_bf16(v1[0], v1[1]); w.w = cvt_pk_bf16(v1[2], v1[3]);
;                     *(u32x4*)(rowp + bj * HALF) = w; }
.LBB0_384:
	v_cvt_pk_bf16_f32 v90, v90, v91
	v_cvt_pk_bf16_f32 v91, v86, v87
	v_cvt_pk_bf16_f32 v92, v82, v83
	v_cvt_pk_bf16_f32 v93, v88, v89
	global_store_dwordx4 v[84:85], v[90:93], off offset:256
	s_and_b64 vcc, exec, s[42:43]
	s_nop 1
	v_cvt_f32_u32_e32 v83, v199
	v_cvt_f32_u32_e32 v82, v198
	v_fmamk_f32 v82, v83, 0x4f800000, v82
	v_fmamk_f32 v82, v82, 0x30800000, v229
	v_rsq_f32_e32 v82, v82
	s_nop 0
	v_pk_mul_f32 v[86:87], v[78:79], v[82:83] op_sel_hi:[1,0]
	v_pk_mul_f32 v[90:91], v[76:77], v[82:83] op_sel_hi:[1,0]
	v_pk_mul_f32 v[88:89], v[74:75], v[82:83] op_sel_hi:[1,0]
	v_pk_mul_f32 v[92:93], v[72:73], v[82:83] op_sel_hi:[1,0]
	s_cbranch_vccnz .LBB0_386
	v_max_f32_e32 v84, 0, v90
	v_max_f32_e32 v92, 0, v92
	v_max_f32_e32 v85, 0, v91
	v_max_f32_e32 v93, 0, v93
	v_max_f32_e32 v86, 0, v86
	v_max_f32_e32 v88, 0, v88
	v_max_f32_e32 v87, 0, v87
	v_max_f32_e32 v89, 0, v89
	v_pk_mul_f32 v[90:91], v[84:85], v[84:85]
	v_pk_mul_f32 v[86:87], v[86:87], v[86:87]
	v_pk_mul_f32 v[92:93], v[92:93], v[92:93]
	v_pk_mul_f32 v[88:89], v[88:89], v[88:89]

; __device__ __forceinline__ unsigned cvt_pk_bf16(float lo, float hi) { unsigned r; asm volatile("v_cvt_pk_bf16_f32 %0, %1, %2" : "=v"(r) : "v"(lo), "v"(hi)); return r; }
;     __device__ __forceinline__ void operator()(const f32x4 (&acc)[2][2][4][2], const Unit& u, int wr, int wc, int fr, int fq) const {
;     ...
;                 bf16_t* rowp = O + (size_t)r * ldc + colt + wc * 32 + 8 * fq;
; #pragma unroll
;                 for (int bj = 0; bj < 2; ++bj) { f32x4 v0 = acc[ai][bj][m][0] * rs, v1 = acc[ai][bj][m][1] * rs;
;                     if (mode == 2) {
; #pragma unroll
;                         for (int e = 0; e < 4; ++e) { float a = fmaxf(v0[e], 0.f), b = fmaxf(v1[e], 0.f); v0[e] = a * a; v1[e] = b * b; } }
;                     if (mode == 1 && colt >= 2048) {
; #pragma unroll
;                         for (int e = 0; e < 4; ++e) { v0[e] = __builtin_amdgcn_rcpf(1.0f + __builtin_amdgcn_exp2f(-1.4426950408889634f * v0[e])); v1[e] = __builtin_amdgcn_rcpf(1.0f + __builtin_amdgcn_exp2f(-1.4426950408889634f * v1[e])); } }
;                     u32x4 w; w.x = cvt_pk_bf16(v0[0], v0[1]); w.y = cvt_pk_bf16(v0[2], v0[3]); w.z = cvt_pk_bf16(v1[0], v1[1]); w.w = cvt_pk_bf16(v1[2], v1[3]);
;                     *(u32x4*)(rowp + bj * HALF) = w; }
.LBB0_388:
	v_or_b32_e32 v84, 48, v160
	v_mad_i64_i32 v[84:85], s[88:89], s54, v84, 0
	v_lshl_add_u64 v[84:85], v[84:85], 1, s[28:29]
	v_lshl_add_u64 v[84:85], s[76:77], 1, v[84:85]
	v_lshl_add_u64 v[84:85], v[84:85], 0, s[34:35]
	v_mov_b32_e32 v83, v82
	v_lshl_add_u64 v[84:85], v[84:85], 0, v[112:113]
	v_cvt_pk_bf16_f32 v90, v90, v91
	v_cvt_pk_bf16_f32 v91, v86, v87
	v_cvt_pk_bf16_f32 v92, v92, v93
	v_cvt_pk_bf16_f32 v93, v88, v89
	v_mov_b32_e32 v88, v82
	v_mov_b32_e32 v89, v82
	global_store_dwordx4 v[84:85], v[90:93], off
	v_pk_mul_f32 v[86:87], v[70:71], v[88:89]
	v_pk_mul_f32 v[88:89], v[66:67], v[88:89]
	v_pk_mul_f32 v[90:91], v[68:69], v[82:83]
	s_and_b64 vcc, exec, s[42:43]
	v_pk_mul_f32 v[82:83], v[64:65], v[82:83]
	s_cbranch_vccnz .LBB0_390
	v_max_f32_e32 v90, 0, v90
	v_max_f32_e32 v82, 0, v82
	v_max_f32_e32 v91, 0, v91
	v_max_f32_e32 v83, 0, v83
	v_max_f32_e32 v86, 0, v86
	v_max_f32_e32 v88, 0, v88
	v_max_f32_e32 v87, 0, v87
	v_max_f32_e32 v89, 0, v89
	v_pk_mul_f32 v[90:91], v[90:91], v[90:91]
	v_pk_mul_f32 v[86:87], v[86:87], v[86:87]
	v_pk_mul_f32 v[82:83], v[82:83], v[82:83]
	v_pk_mul_f32 v[88:89], v[88:89], v[88:89]

; __device__ __forceinline__ unsigned cvt_pk_bf16(float lo, float hi) { unsigned r; asm volatile("v_cvt_pk_bf16_f32 %0, %1, %2" : "=v"(r) : "v"(lo), "v"(hi)); return r; }
;     __device__ __forceinline__ void operator()(const f32x4 (&acc)[2][2][4][2], const Unit& u, int wr, int wc, int fr, int fq) const {
;     ...
;                 const int r = row0 + ai * HALF + m * 16;
;                 const float rs = __builtin_amdgcn_rsqf((float)ss[r] * (1.0f / 1048576.0f) * (1.0f / 1024.0f) + EPS);
;                 bf16_t* rowp = O + (size_t)r * ldc + colt + wc * 32 + 8 * fq;
; #pragma unroll
;                 for (int bj = 0; bj < 2; ++bj) { f32x4 v0 = acc[ai][bj][m][0] * rs, v1 = acc[ai][bj][m][1] * rs;
;                     if (mode == 2) {
; #pragma unroll
;                         for (int e = 0; e < 4; ++e) { float a = fmaxf(v0[e], 0.f), b = fmaxf(v1[e], 0.f); v0[e] = a * a; v1[e] = b * b; } }
;                     if (mode == 1 && colt >= 2048) {
; #pragma unroll
;                         for (int e = 0; e < 4; ++e) { v0[e] = __builtin_amdgcn_rcpf(1.0f + __builtin_amdgcn_exp2f(-1.4426950408889634f * v0[e])); v1[e] = __builtin_amdgcn_rcpf(1.0f + __builtin_amdgcn_exp2f(-1.4426950408889634f * v1[e])); } }
;                     u32x4 w; w.x = cvt_pk_bf16(v0[0], v0[1]); w.y = cvt_pk_bf16(v0[2], v0[3]); w.z = cvt_pk_bf16(v1[0], v1[1]); w.w = cvt_pk_bf16(v1[2], v1[3]);
;                     *(u32x4*)(rowp + bj * HALF) = w; }
.LBB0_392:
	v_cvt_pk_bf16_f32 v90, v90, v91
	v_cvt_pk_bf16_f32 v91, v86, v87
	v_cvt_pk_bf16_f32 v92, v82, v83
	v_cvt_pk_bf16_f32 v93, v88, v89
	global_store_dwordx4 v[84:85], v[90:93], off offset:256
	s_and_b64 vcc, exec, s[42:43]
	s_nop 1
	v_cvt_f32_u32_e32 v83, v201
	v_cvt_f32_u32_e32 v82, v200
	v_fmamk_f32 v82, v83, 0x4f800000, v82
	v_fmamk_f32 v82, v82, 0x30800000, v229
	v_rsq_f32_e32 v82, v82
	s_nop 0
	v_pk_mul_f32 v[86:87], v[62:63], v[82:83] op_sel_hi:[1,0]
	v_pk_mul_f32 v[90:91], v[60:61], v[82:83] op_sel_hi:[1,0]
	v_pk_mul_f32 v[88:89], v[58:59], v[82:83] op_sel_hi:[1,0]
	v_pk_mul_f32 v[92:93], v[56:57], v[82:83] op_sel_hi:[1,0]
	s_cbranch_vccnz .LBB0_394
	v_max_f32_e32 v84, 0, v90
	v_max_f32_e32 v92, 0, v92
	v_max_f32_e32 v85, 0, v91
	v_max_f32_e32 v93, 0, v93
	v_max_f32_e32 v86, 0, v86
	v_max_f32_e32 v88, 0, v88
	v_max_f32_e32 v87, 0, v87
	v_max_f32_e32 v89, 0, v89
	v_pk_mul_f32 v[90:91], v[84:85], v[84:85]
	v_pk_mul_f32 v[86:87], v[86:87], v[86:87]
	v_pk_mul_f32 v[92:93], v[92:93], v[92:93]
	v_pk_mul_f32 v[88:89], v[88:89], v[88:89]

; __device__ __forceinline__ unsigned cvt_pk_bf16(float lo, float hi) { unsigned r; asm volatile("v_cvt_pk_bf16_f32 %0, %1, %2" : "=v"(r) : "v"(lo), "v"(hi)); return r; }
;     __device__ __forceinline__ void operator()(const f32x4 (&acc)[2][2][4][2], const Unit& u, int wr, int wc, int fr, int fq) const {
;     ...
;                 bf16_t* rowp = O + (size_t)r * ldc + colt + wc * 32 + 8 * fq;
; #pragma unroll
;                 for (int bj = 0; bj < 2; ++bj) { f32x4 v0 = acc[ai][bj][m][0] * rs, v1 = acc[ai][bj][m][1] * rs;
;                     if (mode == 2) {
; #pragma unroll
;                         for (int e = 0; e < 4; ++e) { float a = fmaxf(v0[e], 0.f), b = fmaxf(v1[e], 0.f); v0[e] = a * a; v1[e] = b * b; } }
;                     if (mode == 1 && colt >= 2048) {
; #pragma unroll
;                         for (int e = 0; e < 4; ++e) { v0[e] = __builtin_amdgcn_rcpf(1.0f + __builtin_amdgcn_exp2f(-1.4426950408889634f * v0[e])); v1[e] = __builtin_amdgcn_rcpf(1.0f + __builtin_amdgcn_exp2f(-1.4426950408889634f * v1[e])); } }
;                     u32x4 w; w.x = cvt_pk_bf16(v0[0], v0[1]); w.y = cvt_pk_bf16(v0[2], v0[3]); w.z = cvt_pk_bf16(v1[0], v1[1]); w.w = cvt_pk_bf16(v1[2], v1[3]);
;                     *(u32x4*)(rowp + bj * HALF) = w; }
.LBB0_396:
	v_add_u32_e32 v84, 0x80, v160
	v_mad_i64_i32 v[84:85], s[88:89], s54, v84, 0
	v_lshl_add_u64 v[84:85], v[84:85], 1, s[28:29]
	v_lshl_add_u64 v[84:85], s[76:77], 1, v[84:85]
	v_lshl_add_u64 v[84:85], v[84:85], 0, s[34:35]
	v_mov_b32_e32 v83, v82
	v_lshl_add_u64 v[84:85], v[84:85], 0, v[112:113]
	v_cvt_pk_bf16_f32 v90, v90, v91
	v_cvt_pk_bf16_f32 v91, v86, v87
	v_cvt_pk_bf16_f32 v92, v92, v93
	v_cvt_pk_bf16_f32 v93, v88, v89
	v_mov_b32_e32 v88, v82
	v_mov_b32_e32 v89, v82
	global_store_dwordx4 v[84:85], v[90:93], off
	v_pk_mul_f32 v[86:87], v[54:55], v[88:89]
	v_pk_mul_f32 v[88:89], v[50:51], v[88:89]
	v_pk_mul_f32 v[90:91], v[52:53], v[82:83]
	s_and_b64 vcc, exec, s[42:43]
	v_pk_mul_f32 v[82:83], v[48:49], v[82:83]
	s_cbranch_vccnz .LBB0_398
	v_max_f32_e32 v90, 0, v90
	v_max_f32_e32 v82, 0, v82
	v_max_f32_e32 v91, 0, v91
	v_max_f32_e32 v83, 0, v83
	v_max_f32_e32 v86, 0, v86
	v_max_f32_e32 v88, 0, v88
	v_max_f32_e32 v87, 0, v87
	v_max_f32_e32 v89, 0, v89
	v_pk_mul_f32 v[90:91], v[90:91], v[90:91]
	v_pk_mul_f32 v[86:87], v[86:87], v[86:87]
	v_pk_mul_f32 v[82:83], v[82:83], v[82:83]
	v_pk_mul_f32 v[88:89], v[88:89], v[88:89]

; __device__ __forceinline__ unsigned cvt_pk_bf16(float lo, float hi) { unsigned r; asm volatile("v_cvt_pk_bf16_f32 %0, %1, %2" : "=v"(r) : "v"(lo), "v"(hi)); return r; }
;     __device__ __forceinline__ void operator()(const f32x4 (&acc)[2][2][4][2], const Unit& u, int wr, int wc, int fr, int fq) const {
;     ...
;                 const int r = row0 + ai * HALF + m * 16;
;                 const float rs = __builtin_amdgcn_rsqf((float)ss[r] * (1.0f / 1048576.0f) * (1.0f / 1024.0f) + EPS);
;                 bf16_t* rowp = O + (size_t)r * ldc + colt + wc * 32 + 8 * fq;
; #pragma unroll
;                 for (int bj = 0; bj < 2; ++bj) { f32x4 v0 = acc[ai][bj][m][0] * rs, v1 = acc[ai][bj][m][1] * rs;
;                     if (mode == 2) {
; #pragma unroll
;                         for (int e = 0; e < 4; ++e) { float a = fmaxf(v0[e], 0.f), b = fmaxf(v1[e], 0.f); v0[e] = a * a; v1[e] = b * b; } }
;                     if (mode == 1 && colt >= 2048) {
; #pragma unroll
;                         for (int e = 0; e < 4; ++e) { v0[e] = __builtin_amdgcn_rcpf(1.0f + __builtin_amdgcn_exp2f(-1.4426950408889634f * v0[e])); v1[e] = __builtin_amdgcn_rcpf(1.0f + __builtin_amdgcn_exp2f(-1.4426950408889634f * v1[e])); } }
;                     u32x4 w; w.x = cvt_pk_bf16(v0[0], v0[1]); w.y = cvt_pk_bf16(v0[2], v0[3]); w.z = cvt_pk_bf16(v1[0], v1[1]); w.w = cvt_pk_bf16(v1[2], v1[3]);
;                     *(u32x4*)(rowp + bj * HALF) = w; }
.LBB0_400:
	v_cvt_pk_bf16_f32 v90, v90, v91
	v_cvt_pk_bf16_f32 v91, v86, v87
	v_cvt_pk_bf16_f32 v92, v82, v83
	v_cvt_pk_bf16_f32 v93, v88, v89
	global_store_dwordx4 v[84:85], v[90:93], off offset:256
	s_and_b64 vcc, exec, s[42:43]
	s_nop 1
	v_cvt_f32_u32_e32 v83, v203
	v_cvt_f32_u32_e32 v82, v202
	v_fmamk_f32 v82, v83, 0x4f800000, v82
	v_fmamk_f32 v82, v82, 0x30800000, v229
	v_rsq_f32_e32 v82, v82
	s_nop 0
	v_pk_mul_f32 v[86:87], v[46:47], v[82:83] op_sel_hi:[1,0]
	v_pk_mul_f32 v[90:91], v[44:45], v[82:83] op_sel_hi:[1,0]
	v_pk_mul_f32 v[88:89], v[42:43], v[82:83] op_sel_hi:[1,0]
	v_pk_mul_f32 v[92:93], v[40:41], v[82:83] op_sel_hi:[1,0]
	s_cbranch_vccnz .LBB0_402
	v_max_f32_e32 v84, 0, v90
	v_max_f32_e32 v92, 0, v92
	v_max_f32_e32 v85, 0, v91
	v_max_f32_e32 v93, 0, v93
	v_max_f32_e32 v86, 0, v86
	v_max_f32_e32 v88, 0, v88
	v_max_f32_e32 v87, 0, v87
	v_max_f32_e32 v89, 0, v89
	v_pk_mul_f32 v[90:91], v[84:85], v[84:85]
	v_pk_mul_f32 v[86:87], v[86:87], v[86:87]
	v_pk_mul_f32 v[92:93], v[92:93], v[92:93]
	v_pk_mul_f32 v[88:89], v[88:89], v[88:89]

; __device__ __forceinline__ unsigned cvt_pk_bf16(float lo, float hi) { unsigned r; asm volatile("v_cvt_pk_bf16_f32 %0, %1, %2" : "=v"(r) : "v"(lo), "v"(hi)); return r; }
;     __device__ __forceinline__ void operator()(const f32x4 (&acc)[2][2][4][2], const Unit& u, int wr, int wc, int fr, int fq) const {
;     ...
;                 bf16_t* rowp = O + (size_t)r * ldc + colt + wc * 32 + 8 * fq;
; #pragma unroll
;                 for (int bj = 0; bj < 2; ++bj) { f32x4 v0 = acc[ai][bj][m][0] * rs, v1 = acc[ai][bj][m][1] * rs;
;                     if (mode == 2) {
; #pragma unroll
;                         for (int e = 0; e < 4; ++e) { float a = fmaxf(v0[e], 0.f), b = fmaxf(v1[e], 0.f); v0[e] = a * a; v1[e] = b * b; } }
;                     if (mode == 1 && colt >= 2048) {
; #pragma unroll
;                         for (int e = 0; e < 4; ++e) { v0[e] = __builtin_amdgcn_rcpf(1.0f + __builtin_amdgcn_exp2f(-1.4426950408889634f * v0[e])); v1[e] = __builtin_amdgcn_rcpf(1.0f + __builtin_amdgcn_exp2f(-1.4426950408889634f * v1[e])); } }
;                     u32x4 w; w.x = cvt_pk_bf16(v0[0], v0[1]); w.y = cvt_pk_bf16(v0[2], v0[3]); w.z = cvt_pk_bf16(v1[0], v1[1]); w.w = cvt_pk_bf16(v1[2], v1[3]);
;                     *(u32x4*)(rowp + bj * HALF) = w; }
.LBB0_404:
	v_add_u32_e32 v84, 0x90, v160
	v_mad_i64_i32 v[84:85], s[88:89], s54, v84, 0
	v_lshl_add_u64 v[84:85], v[84:85], 1, s[28:29]
	v_lshl_add_u64 v[84:85], s[76:77], 1, v[84:85]
	v_lshl_add_u64 v[84:85], v[84:85], 0, s[34:35]
	v_mov_b32_e32 v83, v82
	v_lshl_add_u64 v[84:85], v[84:85], 0, v[112:113]
	v_cvt_pk_bf16_f32 v90, v90, v91
	v_cvt_pk_bf16_f32 v91, v86, v87
	v_cvt_pk_bf16_f32 v92, v92, v93
	v_cvt_pk_bf16_f32 v93, v88, v89
	v_mov_b32_e32 v88, v82
	v_mov_b32_e32 v89, v82
	global_store_dwordx4 v[84:85], v[90:93], off
	v_pk_mul_f32 v[86:87], v[38:39], v[88:89]
	v_pk_mul_f32 v[88:89], v[34:35], v[88:89]
	v_pk_mul_f32 v[90:91], v[36:37], v[82:83]
	s_and_b64 vcc, exec, s[42:43]
	v_pk_mul_f32 v[82:83], v[32:33], v[82:83]
	s_cbranch_vccnz .LBB0_406
	v_max_f32_e32 v90, 0, v90
	v_max_f32_e32 v82, 0, v82
	v_max_f32_e32 v91, 0, v91
	v_max_f32_e32 v83, 0, v83
	v_max_f32_e32 v86, 0, v86
	v_max_f32_e32 v88, 0, v88
	v_max_f32_e32 v87, 0, v87
	v_max_f32_e32 v89, 0, v89
	v_pk_mul_f32 v[90:91], v[90:91], v[90:91]
	v_pk_mul_f32 v[86:87], v[86:87], v[86:87]
	v_pk_mul_f32 v[82:83], v[82:83], v[82:83]
	v_pk_mul_f32 v[88:89], v[88:89], v[88:89]

; __device__ __forceinline__ unsigned cvt_pk_bf16(float lo, float hi) { unsigned r; asm volatile("v_cvt_pk_bf16_f32 %0, %1, %2" : "=v"(r) : "v"(lo), "v"(hi)); return r; }
;     __device__ __forceinline__ void operator()(const f32x4 (&acc)[2][2][4][2], const Unit& u, int wr, int wc, int fr, int fq) const {
;     ...
;                 const int r = row0 + ai * HALF + m * 16;
;                 const float rs = __builtin_amdgcn_rsqf((float)ss[r] * (1.0f / 1048576.0f) * (1.0f / 1024.0f) + EPS);
;                 bf16_t* rowp = O + (size_t)r * ldc + colt + wc * 32 + 8 * fq;
; #pragma unroll
;                 for (int bj = 0; bj < 2; ++bj) { f32x4 v0 = acc[ai][bj][m][0] * rs, v1 = acc[ai][bj][m][1] * rs;
;                     if (mode == 2) {
; #pragma unroll
;                         for (int e = 0; e < 4; ++e) { float a = fmaxf(v0[e], 0.f), b = fmaxf(v1[e], 0.f); v0[e] = a * a; v1[e] = b * b; } }
;                     if (mode == 1 && colt >= 2048) {
; #pragma unroll
;                         for (int e = 0; e < 4; ++e) { v0[e] = __builtin_amdgcn_rcpf(1.0f + __builtin_amdgcn_exp2f(-1.4426950408889634f * v0[e])); v1[e] = __builtin_amdgcn_rcpf(1.0f + __builtin_amdgcn_exp2f(-1.4426950408889634f * v1[e])); } }
;                     u32x4 w; w.x = cvt_pk_bf16(v0[0], v0[1]); w.y = cvt_pk_bf16(v0[2], v0[3]); w.z = cvt_pk_bf16(v1[0], v1[1]); w.w = cvt_pk_bf16(v1[2], v1[3]);
;                     *(u32x4*)(rowp + bj * HALF) = w; }
.LBB0_408:
	v_cvt_pk_bf16_f32 v90, v90, v91
	v_cvt_pk_bf16_f32 v91, v86, v87
	v_cvt_pk_bf16_f32 v92, v82, v83
	v_cvt_pk_bf16_f32 v93, v88, v89
	global_store_dwordx4 v[84:85], v[90:93], off offset:256
	s_and_b64 vcc, exec, s[42:43]
	s_nop 1
	v_cvt_f32_u32_e32 v83, v205
	v_cvt_f32_u32_e32 v82, v204
	v_fmamk_f32 v82, v83, 0x4f800000, v82
	v_fmamk_f32 v82, v82, 0x30800000, v229
	v_rsq_f32_e32 v82, v82
	s_nop 0
	v_pk_mul_f32 v[86:87], v[30:31], v[82:83] op_sel_hi:[1,0]
	v_pk_mul_f32 v[90:91], v[28:29], v[82:83] op_sel_hi:[1,0]
	v_pk_mul_f32 v[88:89], v[26:27], v[82:83] op_sel_hi:[1,0]
	v_pk_mul_f32 v[92:93], v[24:25], v[82:83] op_sel_hi:[1,0]
	s_cbranch_vccnz .LBB0_410
	v_max_f32_e32 v84, 0, v90
	v_max_f32_e32 v92, 0, v92
	v_max_f32_e32 v85, 0, v91
	v_max_f32_e32 v93, 0, v93
	v_max_f32_e32 v86, 0, v86
	v_max_f32_e32 v88, 0, v88
	v_max_f32_e32 v87, 0, v87
	v_max_f32_e32 v89, 0, v89
	v_pk_mul_f32 v[90:91], v[84:85], v[84:85]
	v_pk_mul_f32 v[86:87], v[86:87], v[86:87]
	v_pk_mul_f32 v[92:93], v[92:93], v[92:93]
	v_pk_mul_f32 v[88:89], v[88:89], v[88:89]

; __device__ __forceinline__ unsigned cvt_pk_bf16(float lo, float hi) { unsigned r; asm volatile("v_cvt_pk_bf16_f32 %0, %1, %2" : "=v"(r) : "v"(lo), "v"(hi)); return r; }
;     __device__ __forceinline__ void operator()(const f32x4 (&acc)[2][2][4][2], const Unit& u, int wr, int wc, int fr, int fq) const {
;     ...
;                 bf16_t* rowp = O + (size_t)r * ldc + colt + wc * 32 + 8 * fq;
; #pragma unroll
;                 for (int bj = 0; bj < 2; ++bj) { f32x4 v0 = acc[ai][bj][m][0] * rs, v1 = acc[ai][bj][m][1] * rs;
;                     if (mode == 2) {
; #pragma unroll
;                         for (int e = 0; e < 4; ++e) { float a = fmaxf(v0[e], 0.f), b = fmaxf(v1[e], 0.f); v0[e] = a * a; v1[e] = b * b; } }
;                     if (mode == 1 && colt >= 2048) {
; #pragma unroll
;                         for (int e = 0; e < 4; ++e) { v0[e] = __builtin_amdgcn_rcpf(1.0f + __builtin_amdgcn_exp2f(-1.4426950408889634f * v0[e])); v1[e] = __builtin_amdgcn_rcpf(1.0f + __builtin_amdgcn_exp2f(-1.4426950408889634f * v1[e])); } }
;                     u32x4 w; w.x = cvt_pk_bf16(v0[0], v0[1]); w.y = cvt_pk_bf16(v0[2], v0[3]); w.z = cvt_pk_bf16(v1[0], v1[1]); w.w = cvt_pk_bf16(v1[2], v1[3]);
;                     *(u32x4*)(rowp + bj * HALF) = w; }
.LBB0_412:
	v_add_u32_e32 v84, 0xa0, v160
	v_mad_i64_i32 v[84:85], s[88:89], s54, v84, 0
	v_lshl_add_u64 v[84:85], v[84:85], 1, s[28:29]
	v_lshl_add_u64 v[84:85], s[76:77], 1, v[84:85]
	v_lshl_add_u64 v[84:85], v[84:85], 0, s[34:35]
	v_mov_b32_e32 v83, v82
	v_lshl_add_u64 v[84:85], v[84:85], 0, v[112:113]
	v_cvt_pk_bf16_f32 v90, v90, v91
	v_cvt_pk_bf16_f32 v91, v86, v87
	v_cvt_pk_bf16_f32 v92, v92, v93
	v_cvt_pk_bf16_f32 v93, v88, v89
	v_mov_b32_e32 v88, v82
	v_mov_b32_e32 v89, v82
	global_store_dwordx4 v[84:85], v[90:93], off
	v_pk_mul_f32 v[86:87], v[22:23], v[88:89]
	v_pk_mul_f32 v[88:89], v[18:19], v[88:89]
	v_pk_mul_f32 v[90:91], v[20:21], v[82:83]
	s_and_b64 vcc, exec, s[42:43]
	v_pk_mul_f32 v[82:83], v[16:17], v[82:83]
	s_cbranch_vccnz .LBB0_414
	v_max_f32_e32 v90, 0, v90
	v_max_f32_e32 v82, 0, v82
	v_max_f32_e32 v91, 0, v91
	v_max_f32_e32 v83, 0, v83
	v_max_f32_e32 v86, 0, v86
	v_max_f32_e32 v88, 0, v88
	v_max_f32_e32 v87, 0, v87
	v_max_f32_e32 v89, 0, v89
	v_pk_mul_f32 v[90:91], v[90:91], v[90:91]
	v_pk_mul_f32 v[86:87], v[86:87], v[86:87]
	v_pk_mul_f32 v[82:83], v[82:83], v[82:83]
	v_pk_mul_f32 v[88:89], v[88:89], v[88:89]

; __device__ __forceinline__ unsigned cvt_pk_bf16(float lo, float hi) { unsigned r; asm volatile("v_cvt_pk_bf16_f32 %0, %1, %2" : "=v"(r) : "v"(lo), "v"(hi)); return r; }
;     __device__ __forceinline__ void operator()(const f32x4 (&acc)[2][2][4][2], const Unit& u, int wr, int wc, int fr, int fq) const {
;     ...
;                 const int r = row0 + ai * HALF + m * 16;
;                 const float rs = __builtin_amdgcn_rsqf((float)ss[r] * (1.0f / 1048576.0f) * (1.0f / 1024.0f) + EPS);
;                 bf16_t* rowp = O + (size_t)r * ldc + colt + wc * 32 + 8 * fq;
; #pragma unroll
;                 for (int bj = 0; bj < 2; ++bj) { f32x4 v0 = acc[ai][bj][m][0] * rs, v1 = acc[ai][bj][m][1] * rs;
;                     if (mode == 2) {
; #pragma unroll
;                         for (int e = 0; e < 4; ++e) { float a = fmaxf(v0[e], 0.f), b = fmaxf(v1[e], 0.f); v0[e] = a * a; v1[e] = b * b; } }
;                     if (mode == 1 && colt >= 2048) {
; #pragma unroll
;                         for (int e = 0; e < 4; ++e) { v0[e] = __builtin_amdgcn_rcpf(1.0f + __builtin_amdgcn_exp2f(-1.4426950408889634f * v0[e])); v1[e] = __builtin_amdgcn_rcpf(1.0f + __builtin_amdgcn_exp2f(-1.4426950408889634f * v1[e])); } }
;                     u32x4 w; w.x = cvt_pk_bf16(v0[0], v0[1]); w.y = cvt_pk_bf16(v0[2], v0[3]); w.z = cvt_pk_bf16(v1[0], v1[1]); w.w = cvt_pk_bf16(v1[2], v1[3]);
;                     *(u32x4*)(rowp + bj * HALF) = w; }
.LBB0_416:
	v_cvt_pk_bf16_f32 v90, v90, v91
	v_cvt_pk_bf16_f32 v91, v86, v87
	v_cvt_pk_bf16_f32 v92, v82, v83
	v_cvt_pk_bf16_f32 v93, v88, v89
	global_store_dwordx4 v[84:85], v[90:93], off offset:256
	s_and_b64 vcc, exec, s[42:43]
	s_nop 1
	v_cvt_f32_u32_e32 v81, v207
	v_cvt_f32_u32_e32 v80, v206
	v_fmamk_f32 v80, v81, 0x4f800000, v80
	v_fmamk_f32 v80, v80, 0x30800000, v229
	v_rsq_f32_e32 v80, v80
	s_nop 0
	v_pk_mul_f32 v[84:85], v[14:15], v[80:81] op_sel_hi:[1,0]
	v_pk_mul_f32 v[88:89], v[12:13], v[80:81] op_sel_hi:[1,0]
	v_pk_mul_f32 v[86:87], v[10:11], v[80:81] op_sel_hi:[1,0]
	v_pk_mul_f32 v[90:91], v[8:9], v[80:81] op_sel_hi:[1,0]
	s_cbranch_vccnz .LBB0_418
	v_max_f32_e32 v82, 0, v88
	v_max_f32_e32 v90, 0, v90
	v_max_f32_e32 v83, 0, v89
	v_max_f32_e32 v91, 0, v91
	v_max_f32_e32 v84, 0, v84
	v_max_f32_e32 v86, 0, v86
	v_max_f32_e32 v85, 0, v85
	v_max_f32_e32 v87, 0, v87
	v_pk_mul_f32 v[88:89], v[82:83], v[82:83]
	v_pk_mul_f32 v[84:85], v[84:85], v[84:85]
	v_pk_mul_f32 v[90:91], v[90:91], v[90:91]
	v_pk_mul_f32 v[86:87], v[86:87], v[86:87]

; __device__ __forceinline__ unsigned cvt_pk_bf16(float lo, float hi) { unsigned r; asm volatile("v_cvt_pk_bf16_f32 %0, %1, %2" : "=v"(r) : "v"(lo), "v"(hi)); return r; }
;     __device__ __forceinline__ void operator()(const f32x4 (&acc)[2][2][4][2], const Unit& u, int wr, int wc, int fr, int fq) const {
;     ...
;                 bf16_t* rowp = O + (size_t)r * ldc + colt + wc * 32 + 8 * fq;
; #pragma unroll
;                 for (int bj = 0; bj < 2; ++bj) { f32x4 v0 = acc[ai][bj][m][0] * rs, v1 = acc[ai][bj][m][1] * rs;
;                     if (mode == 2) {
; #pragma unroll
;                         for (int e = 0; e < 4; ++e) { float a = fmaxf(v0[e], 0.f), b = fmaxf(v1[e], 0.f); v0[e] = a * a; v1[e] = b * b; } }
;                     if (mode == 1 && colt >= 2048) {
; #pragma unroll
;                         for (int e = 0; e < 4; ++e) { v0[e] = __builtin_amdgcn_rcpf(1.0f + __builtin_amdgcn_exp2f(-1.4426950408889634f * v0[e])); v1[e] = __builtin_amdgcn_rcpf(1.0f + __builtin_amdgcn_exp2f(-1.4426950408889634f * v1[e])); } }
;                     u32x4 w; w.x = cvt_pk_bf16(v0[0], v0[1]); w.y = cvt_pk_bf16(v0[2], v0[3]); w.z = cvt_pk_bf16(v1[0], v1[1]); w.w = cvt_pk_bf16(v1[2], v1[3]);
;                     *(u32x4*)(rowp + bj * HALF) = w; }
.LBB0_420:
	v_add_u32_e32 v82, 0xb0, v160
	v_mad_i64_i32 v[82:83], s[88:89], s54, v82, 0
	v_lshl_add_u64 v[82:83], v[82:83], 1, s[28:29]
	v_lshl_add_u64 v[82:83], s[76:77], 1, v[82:83]
	v_lshl_add_u64 v[82:83], v[82:83], 0, s[34:35]
	v_mov_b32_e32 v81, v80
	v_lshl_add_u64 v[82:83], v[82:83], 0, v[112:113]
	v_cvt_pk_bf16_f32 v88, v88, v89
	v_cvt_pk_bf16_f32 v89, v84, v85
	v_mov_b32_e32 v84, v80
	v_mov_b32_e32 v85, v80
	v_cvt_pk_bf16_f32 v90, v90, v91
	v_cvt_pk_bf16_f32 v91, v86, v87
	global_store_dwordx4 v[82:83], v[88:91], off
	v_pk_mul_f32 v[86:87], v[6:7], v[84:85]
	v_pk_mul_f32 v[84:85], v[2:3], v[84:85]
	v_pk_mul_f32 v[88:89], v[4:5], v[80:81]
	s_and_b64 vcc, exec, s[42:43]
	v_pk_mul_f32 v[80:81], v[0:1], v[80:81]
	s_cbranch_vccnz .LBB0_422
	v_max_f32_e32 v88, 0, v88
	v_max_f32_e32 v80, 0, v80
	v_max_f32_e32 v89, 0, v89
	v_max_f32_e32 v81, 0, v81
	v_max_f32_e32 v86, 0, v86
	v_max_f32_e32 v84, 0, v84
	v_max_f32_e32 v87, 0, v87
	v_max_f32_e32 v85, 0, v85
	v_pk_mul_f32 v[88:89], v[88:89], v[88:89]
	v_pk_mul_f32 v[86:87], v[86:87], v[86:87]
	v_pk_mul_f32 v[80:81], v[80:81], v[80:81]
	v_pk_mul_f32 v[84:85], v[84:85], v[84:85]

; __device__ __forceinline__ unsigned cvt_pk_bf16(float lo, float hi) { unsigned r; asm volatile("v_cvt_pk_bf16_f32 %0, %1, %2" : "=v"(r) : "v"(lo), "v"(hi)); return r; }
;     __device__ __forceinline__ void operator()(const f32x4 (&acc)[2][2][4][2], const Unit& u, int wr, int wc, int fr, int fq) const {
;     ...
;             const int blk = colt >> 10, g = blk % 3, sec = blk / 3; const int dsh = (g == 0) ? 0 : (g == 1 ? 2 : 4); const int cin = (colt & 1023) + 64 * wc + 8 * fq;
;             f32x4 gn[2][2];
;             const float* gp = (sec == 0) ? qg + g * 64 : kg + g * 64;
; #pragma unroll
;             for (int bj = 0; bj < 2; ++bj)
; #pragma unroll
;                 for (int n = 0; n < 2; ++n) gn[bj][n] = (sec < 2) ? *(const f32x4*)(gp + 32 * bj + 8 * fq + 4 * n) : (f32x4){1.f, 1.f, 1.f, 1.f};
;             const float qsc = (sec == 0) ? 0.125f * 1.4426950408889634f : 1.0f;
; #pragma unroll
;             for (int ai = 0; ai < 2; ++ai)
; #pragma unroll
;                 for (int m = 0; m < 4; ++m) {
;                     const int r = row0 + ai * HALF + m * 16;
;                     const float rs = __builtin_amdgcn_rsqf((float)ss[r] * (1.0f / 1048576.0f) * (1.0f / 1024.0f) + EPS);
;                     f32x4 v[2][2]; float sq = 0.f;
; #pragma unroll
;                     for (int bj = 0; bj < 2; ++bj)
; #pragma unroll
;                         for (int n = 0; n < 2; ++n) { v[bj][n] = acc[ai][bj][m][n] * rs; sq += (v[bj][n][0] * v[bj][n][0] + v[bj][n][1] * v[bj][n][1]) + (v[bj][n][2] * v[bj][n][2] + v[bj][n][3] * v[bj][n][3]); }
;                     sq = x16_sum(sq); sq = x32_sum(sq);
;                     const float r2 = (sec < 2) ? qsc * __builtin_amdgcn_rsqf(sq * (1.0f / 64.0f) + EPS) : 1.0f;
;                     const int bl = r >> 13, t = r & 8191; const int pr = (bl << 13) + ((t & ((1 << dsh) - 1)) << (13 - dsh)) + (t >> dsh);
;                     bf16_t* rowp = O + (size_t)blk * SEC + (size_t)pr * 1024 + cin;
; #pragma unroll
;                     for (int bj = 0; bj < 2; ++bj) { const f32x4 v0 = v[bj][0] * gn[bj][0] * r2, v1 = v[bj][1] * gn[bj][1] * r2;
;                         u32x4 w; w.x = cvt_pk_bf16(v0[0], v0[1]); w.y = cvt_pk_bf16(v0[2], v0[3]); w.z = cvt_pk_bf16(v1[0], v1[1]); w.w = cvt_pk_bf16(v1[2], v1[3]);
;                         *(u32x4*)(rowp + bj * 32) = w; }
.LBB0_433:
	s_mov_b32 vcc_lo, 0xff00ff00
	s_mov_b32 vcc_hi, 0xff00ff00
	v_mov_b32_e32 v219, 0
	v_mov_b32_e32 v221, 0
	s_nop 1
	v_cndmask_b32_e64 v218, 0, 64, vcc
	v_cndmask_b32_e64 v220, 64, 0, vcc
	v_lshl_add_u64 v[162:163], v[160:161], 3, s[48:49]
	s_cmp_eq_u32 s2, 1
	s_cselect_b32 s34, 2, 4
	s_cmp_lg_u32 s2, 0
	v_cndmask_b32_e64 v171, 1.0, v234, s[0:1]
	s_cselect_b32 s34, s34, 0
	s_sub_i32 s42, 13, s34
	s_and_b32 s43, s69, 0xffffe000
	s_ashr_i32 s89, s88, 31
	s_and_b32 s2, s76, 0x300
	s_lshl_b64 s[0:1], s[88:89], 25
	s_add_u32 s0, s28, s0
	v_or_b32_e32 v172, s2, v169
	s_addc_u32 s1, s29, s1
	s_movk_i32 s2, 0x1fdf
	s_waitcnt vmcnt(0)
	s_nop 1
	v_cvt_f32_u32_e32 v165, v193
	v_cvt_f32_u32_e32 v164, v192
	v_fmamk_f32 v164, v165, 0x4f800000, v164
	v_fmamk_f32 v164, v164, 0x30800000, v229
	v_rsq_f32_e32 v112, v164
	s_nop 0
	v_pk_mul_f32 v[144:145], v[144:145], v[112:113] op_sel_hi:[1,0]
	v_pk_mul_f32 v[222:223], v[144:145], v[144:145]
	v_pk_mul_f32 v[164:165], v[142:143], v[112:113] op_sel_hi:[1,0]
	v_pk_fma_f32 v[222:223], v[164:165], v[164:165], v[222:223]
	v_pk_mul_f32 v[140:141], v[140:141], v[112:113] op_sel_hi:[1,0]
	v_pk_fma_f32 v[222:223], v[140:141], v[140:141], v[222:223]
	v_pk_mul_f32 v[142:143], v[138:139], v[112:113] op_sel_hi:[1,0]
	v_pk_fma_f32 v[222:223], v[142:143], v[142:143], v[222:223]
	v_pk_mul_f32 v[136:137], v[136:137], v[112:113] op_sel_hi:[1,0]
	v_pk_fma_f32 v[222:223], v[136:137], v[136:137], v[222:223]
	v_pk_mul_f32 v[138:139], v[134:135], v[112:113] op_sel_hi:[1,0]
	v_pk_fma_f32 v[222:223], v[138:139], v[138:139], v[222:223]
	v_pk_mul_f32 v[132:133], v[132:133], v[112:113] op_sel_hi:[1,0]
	v_pk_fma_f32 v[222:223], v[132:133], v[132:133], v[222:223]
	v_pk_mul_f32 v[134:135], v[130:131], v[112:113] op_sel_hi:[1,0]
	v_pk_fma_f32 v[222:223], v[134:135], v[134:135], v[222:223]
	v_add_f32_e32 v112, v222, v223
	v_mov_b32_e32 v130, v112
	s_nop 1
	v_permlane16_swap_b32_e32 v112, v130
	v_add_f32_e32 v112, v112, v130
	v_mov_b32_e32 v130, v112
	s_nop 1
	v_permlane32_swap_b32_e32 v112, v130
	v_add_f32_e32 v112, v112, v130
	v_fmamk_f32 v112, v112, 0x3c800000, v229
	v_rsq_f32_e32 v112, v112
	v_lshlrev_b32_e32 v131, s42, v160
	v_and_b32_e32 v131, 0x1ffe, v131
	v_pk_mul_f32 v[164:165], v[92:93], v[164:165]
	v_mul_f32_e32 v112, v171, v112
	v_cndmask_b32_e64 v130, 1.0, v112, s[40:41]
	v_and_b32_e32 v112, 0x1fcf, v160
	v_lshrrev_b32_e32 v112, s34, v112
	v_or_b32_e32 v112, s43, v112
	v_add_u32_e32 v166, v112, v131
	v_ashrrev_i32_e32 v167, 31, v166
	v_lshlrev_b64 v[166:167], 11, v[166:167]
	v_lshl_add_u64 v[166:167], s[0:1], 0, v[166:167]
	v_lshlrev_b32_e32 v112, 1, v172
	v_pk_mul_f32 v[144:145], v[94:95], v[144:145]
	v_pk_mul_f32 v[142:143], v[88:89], v[142:143]
	v_pk_mul_f32 v[140:141], v[90:91], v[140:141]
	v_lshl_add_u64 v[166:167], v[166:167], 0, v[112:113]
	v_pk_mul_f32 v[144:145], v[144:145], v[130:131] op_sel_hi:[1,0]
	v_pk_mul_f32 v[164:165], v[164:165], v[130:131] op_sel_hi:[1,0]
	v_pk_mul_f32 v[172:173], v[140:141], v[130:131] op_sel_hi:[1,0]
	v_pk_mul_f32 v[142:143], v[142:143], v[130:131] op_sel_hi:[1,0]
	v_cvt_pk_bf16_f32 v184, v164, v165
	v_cvt_pk_bf16_f32 v185, v144, v145
	v_pk_mul_f32 v[134:135], v[80:81], v[134:135]
	v_pk_mul_f32 v[132:133], v[82:83], v[132:133]
	v_cvt_pk_bf16_f32 v186, v142, v143
	v_cvt_pk_bf16_f32 v187, v172, v173
	v_pk_mul_f32 v[138:139], v[84:85], v[138:139]
	v_pk_mul_f32 v[136:137], v[86:87], v[136:137]
	v_pk_mul_f32 v[140:141], v[132:133], v[130:131] op_sel_hi:[1,0]
	v_pk_mul_f32 v[132:133], v[134:135], v[130:131] op_sel_hi:[1,0]
	v_pk_mul_f32 v[136:137], v[136:137], v[130:131] op_sel_hi:[1,0]
	v_pk_mul_f32 v[138:139], v[138:139], v[130:131] op_sel_hi:[1,0]
	s_nop 0
	v_cvt_pk_bf16_f32 v130, v138, v139
	v_cvt_pk_bf16_f32 v131, v136, v137
	v_cvt_pk_bf16_f32 v132, v132, v133
	v_cvt_pk_bf16_f32 v133, v140, v141
	v_mov_b32_dpp v180, v184 row_ror:8 row_mask:0xf bank_mask:0xf
	v_mov_b32_dpp v181, v185 row_ror:8 row_mask:0xf bank_mask:0xf
	v_mov_b32_dpp v182, v186 row_ror:8 row_mask:0xf bank_mask:0xf
	v_mov_b32_dpp v183, v187 row_ror:8 row_mask:0xf bank_mask:0xf
	v_lshl_add_u64 v[212:213], v[166:167], 0, v[218:219]
	v_lshl_add_u64 v[216:217], v[166:167], 0, v[220:221]
	v_mov_b32_dpp v184, v130 row_ror:8 row_mask:0xf bank_mask:0xc
	v_mov_b32_dpp v185, v131 row_ror:8 row_mask:0xf bank_mask:0xc
	v_mov_b32_dpp v186, v132 row_ror:8 row_mask:0xf bank_mask:0xc
	v_mov_b32_dpp v187, v133 row_ror:8 row_mask:0xf bank_mask:0xc
	v_mov_b32_e32 v214, v212
	v_mov_b32_e32 v215, v213
	v_cndmask_b32_e32 v130, v180, v130, vcc
	v_cndmask_b32_e32 v131, v181, v131, vcc
	v_cndmask_b32_e32 v132, v182, v132, vcc
	v_cndmask_b32_e32 v133, v183, v133, vcc
	v_mov_b32_dpp v212, v216 row_ror:8 row_mask:0xf bank_mask:0xc
	v_mov_b32_dpp v213, v217 row_ror:8 row_mask:0xf bank_mask:0xc
	v_mov_b32_dpp v214, v216 row_ror:8 row_mask:0xf bank_mask:0x3
	v_mov_b32_dpp v215, v217 row_ror:8 row_mask:0xf bank_mask:0x3
	s_nop 0
	global_store_dwordx4 v[212:213], v[184:187], off
	global_store_dwordx4 v[214:215], v[130:133], off
	s_nop 1
	v_or_b32_e32 v133, 16, v160
	v_cvt_f32_u32_e32 v131, v195
	v_cvt_f32_u32_e32 v130, v194
	v_fmamk_f32 v130, v131, 0x4f800000, v130
	v_fmamk_f32 v130, v130, 0x30800000, v229
	v_rsq_f32_e32 v132, v130
	s_nop 0
	v_pk_mul_f32 v[128:129], v[128:129], v[132:133] op_sel_hi:[1,0]
	v_pk_mul_f32 v[222:223], v[128:129], v[128:129]
	v_pk_mul_f32 v[130:131], v[126:127], v[132:133] op_sel_hi:[1,0]
	v_pk_fma_f32 v[222:223], v[130:131], v[130:131], v[222:223]
	v_pk_mul_f32 v[124:125], v[124:125], v[132:133] op_sel_hi:[1,0]
	v_pk_fma_f32 v[222:223], v[124:125], v[124:125], v[222:223]
	v_pk_mul_f32 v[126:127], v[122:123], v[132:133] op_sel_hi:[1,0]
; __device__ __forceinline__ unsigned cvt_pk_bf16(float lo, float hi) { unsigned r; asm volatile("v_cvt_pk_bf16_f32 %0, %1, %2" : "=v"(r) : "v"(lo), "v"(hi)); return r; }
; DI float x16_sum(float x) { const unsigned u = __builtin_bit_cast(unsigned, x); auto r = __builtin_amdgcn_permlane16_swap(u, u, false, false); return __builtin_bit_cast(float, (unsigned)r[0]) + __builtin_bit_cast(float, (unsigned)r[1]); }
; DI float x32_sum(float x) { const unsigned u = __builtin_bit_cast(unsigned, x); auto r = __builtin_amdgcn_permlane32_swap(u, u, false, false); return __builtin_bit_cast(float, (unsigned)r[0]) + __builtin_bit_cast(float, (unsigned)r[1]); }
;     __device__ __forceinline__ void operator()(const f32x4 (&acc)[2][2][4][2], const Unit& u, int wr, int wc, int fr, int fq) const {
;     ...
;                     const int r = row0 + ai * HALF + m * 16;
;                     const float rs = __builtin_amdgcn_rsqf((float)ss[r] * (1.0f / 1048576.0f) * (1.0f / 1024.0f) + EPS);
;                     f32x4 v[2][2]; float sq = 0.f;
; #pragma unroll
;                     for (int bj = 0; bj < 2; ++bj)
; #pragma unroll
;                         for (int n = 0; n < 2; ++n) { v[bj][n] = acc[ai][bj][m][n] * rs; sq += (v[bj][n][0] * v[bj][n][0] + v[bj][n][1] * v[bj][n][1]) + (v[bj][n][2] * v[bj][n][2] + v[bj][n][3] * v[bj][n][3]); }
;                     sq = x16_sum(sq); sq = x32_sum(sq);
;                     const float r2 = (sec < 2) ? qsc * __builtin_amdgcn_rsqf(sq * (1.0f / 64.0f) + EPS) : 1.0f;
;                     const int bl = r >> 13, t = r & 8191; const int pr = (bl << 13) + ((t & ((1 << dsh) - 1)) << (13 - dsh)) + (t >> dsh);
;                     bf16_t* rowp = O + (size_t)blk * SEC + (size_t)pr * 1024 + cin;
; #pragma unroll
;                     for (int bj = 0; bj < 2; ++bj) { const f32x4 v0 = v[bj][0] * gn[bj][0] * r2, v1 = v[bj][1] * gn[bj][1] * r2;
;                         u32x4 w; w.x = cvt_pk_bf16(v0[0], v0[1]); w.y = cvt_pk_bf16(v0[2], v0[3]); w.z = cvt_pk_bf16(v1[0], v1[1]); w.w = cvt_pk_bf16(v1[2], v1[3]);
;                         *(u32x4*)(rowp + bj * 32) = w; }
	v_pk_fma_f32 v[222:223], v[126:127], v[126:127], v[222:223]
	v_pk_mul_f32 v[120:121], v[120:121], v[132:133] op_sel_hi:[1,0]
	v_pk_fma_f32 v[222:223], v[120:121], v[120:121], v[222:223]
	v_pk_mul_f32 v[122:123], v[118:119], v[132:133] op_sel_hi:[1,0]
	v_pk_fma_f32 v[222:223], v[122:123], v[122:123], v[222:223]
	v_pk_mul_f32 v[116:117], v[116:117], v[132:133] op_sel_hi:[1,0]
	v_pk_fma_f32 v[222:223], v[116:117], v[116:117], v[222:223]
	v_pk_mul_f32 v[118:119], v[114:115], v[132:133] op_sel_hi:[1,0]
	v_pk_fma_f32 v[222:223], v[118:119], v[118:119], v[222:223]
	v_add_f32_e32 v114, v222, v223
	v_mov_b32_e32 v115, v114
	s_nop 1
	v_permlane16_swap_b32_e32 v114, v115
	v_add_f32_e32 v114, v114, v115
	v_mov_b32_e32 v115, v114
	s_nop 1
	v_permlane32_swap_b32_e32 v114, v115
	v_add_f32_e32 v114, v114, v115
	v_fmamk_f32 v114, v114, 0x3c800000, v229
	v_bitop3_b32 v115, v160, s2, 16 bitop3:0xc8
	v_rsq_f32_e32 v114, v114
	v_lshlrev_b32_e32 v132, s42, v133
	v_lshrrev_b32_e32 v115, s34, v115
	v_and_b32_e32 v132, 0x1ffe, v132
	v_or_b32_e32 v115, s43, v115
	v_add_u32_e32 v132, v115, v132
	v_ashrrev_i32_e32 v133, 31, v132
	v_mul_f32_e32 v114, v171, v114
	v_lshlrev_b64 v[132:133], 11, v[132:133]
	v_cndmask_b32_e64 v114, 1.0, v114, s[40:41]
	v_lshl_add_u64 v[132:133], s[0:1], 0, v[132:133]
	v_pk_mul_f32 v[130:131], v[92:93], v[130:131]
	v_pk_mul_f32 v[128:129], v[94:95], v[128:129]
	v_pk_mul_f32 v[126:127], v[88:89], v[126:127]
	v_pk_mul_f32 v[124:125], v[90:91], v[124:125]
	v_lshl_add_u64 v[132:133], v[132:133], 0, v[112:113]
	v_pk_mul_f32 v[128:129], v[128:129], v[114:115] op_sel_hi:[1,0]
	v_pk_mul_f32 v[130:131], v[130:131], v[114:115] op_sel_hi:[1,0]
	v_pk_mul_f32 v[134:135], v[124:125], v[114:115] op_sel_hi:[1,0]
	v_pk_mul_f32 v[126:127], v[126:127], v[114:115] op_sel_hi:[1,0]
	v_cvt_pk_bf16_f32 v184, v130, v131
	v_cvt_pk_bf16_f32 v185, v128, v129
	v_pk_mul_f32 v[118:119], v[80:81], v[118:119]
	v_pk_mul_f32 v[116:117], v[82:83], v[116:117]
	v_cvt_pk_bf16_f32 v186, v126, v127
	v_cvt_pk_bf16_f32 v187, v134, v135
	v_pk_mul_f32 v[122:123], v[84:85], v[122:123]
	v_pk_mul_f32 v[120:121], v[86:87], v[120:121]
	v_pk_mul_f32 v[124:125], v[116:117], v[114:115] op_sel_hi:[1,0]
	v_pk_mul_f32 v[116:117], v[118:119], v[114:115] op_sel_hi:[1,0]
	v_pk_mul_f32 v[120:121], v[120:121], v[114:115] op_sel_hi:[1,0]
	v_pk_mul_f32 v[122:123], v[122:123], v[114:115] op_sel_hi:[1,0]
	s_movk_i32 s2, 0x1fef
	v_cvt_pk_bf16_f32 v114, v122, v123
	v_cvt_pk_bf16_f32 v115, v120, v121
	v_cvt_pk_bf16_f32 v116, v116, v117
	v_cvt_pk_bf16_f32 v117, v124, v125
	v_mov_b32_dpp v180, v184 row_ror:8 row_mask:0xf bank_mask:0xf
	v_mov_b32_dpp v181, v185 row_ror:8 row_mask:0xf bank_mask:0xf
	v_mov_b32_dpp v182, v186 row_ror:8 row_mask:0xf bank_mask:0xf
	v_mov_b32_dpp v183, v187 row_ror:8 row_mask:0xf bank_mask:0xf
	v_lshl_add_u64 v[212:213], v[132:133], 0, v[218:219]
	v_lshl_add_u64 v[216:217], v[132:133], 0, v[220:221]
	v_mov_b32_dpp v184, v114 row_ror:8 row_mask:0xf bank_mask:0xc
	v_mov_b32_dpp v185, v115 row_ror:8 row_mask:0xf bank_mask:0xc
	v_mov_b32_dpp v186, v116 row_ror:8 row_mask:0xf bank_mask:0xc
	v_mov_b32_dpp v187, v117 row_ror:8 row_mask:0xf bank_mask:0xc
	v_mov_b32_e32 v214, v212
	v_mov_b32_e32 v215, v213
	v_cndmask_b32_e32 v114, v180, v114, vcc
	v_cndmask_b32_e32 v115, v181, v115, vcc
	v_cndmask_b32_e32 v116, v182, v116, vcc
	v_cndmask_b32_e32 v117, v183, v117, vcc
	v_mov_b32_dpp v212, v216 row_ror:8 row_mask:0xf bank_mask:0xc
	v_mov_b32_dpp v213, v217 row_ror:8 row_mask:0xf bank_mask:0xc
	v_mov_b32_dpp v214, v216 row_ror:8 row_mask:0xf bank_mask:0x3
	v_mov_b32_dpp v215, v217 row_ror:8 row_mask:0xf bank_mask:0x3
	s_nop 0
	global_store_dwordx4 v[212:213], v[184:187], off
	global_store_dwordx4 v[214:215], v[114:117], off
	s_nop 1
	v_or_b32_e32 v117, 32, v160
	v_cvt_f32_u32_e32 v115, v197
	v_cvt_f32_u32_e32 v114, v196
	v_fmamk_f32 v114, v115, 0x4f800000, v114
	v_fmamk_f32 v114, v114, 0x30800000, v229
	v_rsq_f32_e32 v116, v114
	s_nop 0
	v_pk_mul_f32 v[110:111], v[110:111], v[116:117] op_sel_hi:[1,0]
	v_pk_mul_f32 v[222:223], v[110:111], v[110:111]
	v_pk_mul_f32 v[114:115], v[108:109], v[116:117] op_sel_hi:[1,0]
	v_pk_fma_f32 v[222:223], v[114:115], v[114:115], v[222:223]
	v_pk_mul_f32 v[106:107], v[106:107], v[116:117] op_sel_hi:[1,0]
	v_pk_fma_f32 v[222:223], v[106:107], v[106:107], v[222:223]
	v_pk_mul_f32 v[108:109], v[104:105], v[116:117] op_sel_hi:[1,0]
	v_pk_fma_f32 v[222:223], v[108:109], v[108:109], v[222:223]
	v_pk_mul_f32 v[102:103], v[102:103], v[116:117] op_sel_hi:[1,0]
	v_pk_fma_f32 v[222:223], v[102:103], v[102:103], v[222:223]
	v_pk_mul_f32 v[104:105], v[100:101], v[116:117] op_sel_hi:[1,0]
	v_pk_fma_f32 v[222:223], v[104:105], v[104:105], v[222:223]
	v_pk_mul_f32 v[98:99], v[98:99], v[116:117] op_sel_hi:[1,0]
	v_pk_fma_f32 v[222:223], v[98:99], v[98:99], v[222:223]
	v_pk_mul_f32 v[100:101], v[96:97], v[116:117] op_sel_hi:[1,0]
	v_pk_fma_f32 v[222:223], v[100:101], v[100:101], v[222:223]
	v_add_f32_e32 v96, v222, v223
	v_mov_b32_e32 v97, v96
	s_nop 1
	v_permlane16_swap_b32_e32 v96, v97
	v_add_f32_e32 v96, v96, v97
	v_mov_b32_e32 v97, v96
	s_nop 1
	v_permlane32_swap_b32_e32 v96, v97
	v_add_f32_e32 v96, v96, v97
	v_fmamk_f32 v96, v96, 0x3c800000, v229
	v_bitop3_b32 v97, v160, s2, 32 bitop3:0xc8
	v_rsq_f32_e32 v96, v96
	v_lshlrev_b32_e32 v116, s42, v117
	v_lshrrev_b32_e32 v97, s34, v97
	v_and_b32_e32 v116, 0x1ffe, v116
	v_or_b32_e32 v97, s43, v97
	v_add_u32_e32 v116, v97, v116
	v_ashrrev_i32_e32 v117, 31, v116
	v_mul_f32_e32 v96, v171, v96
	v_lshlrev_b64 v[116:117], 11, v[116:117]
	v_cndmask_b32_e64 v96, 1.0, v96, s[40:41]
	v_lshl_add_u64 v[116:117], s[0:1], 0, v[116:117]
; __device__ __forceinline__ unsigned cvt_pk_bf16(float lo, float hi) { unsigned r; asm volatile("v_cvt_pk_bf16_f32 %0, %1, %2" : "=v"(r) : "v"(lo), "v"(hi)); return r; }
; DI float x16_sum(float x) { const unsigned u = __builtin_bit_cast(unsigned, x); auto r = __builtin_amdgcn_permlane16_swap(u, u, false, false); return __builtin_bit_cast(float, (unsigned)r[0]) + __builtin_bit_cast(float, (unsigned)r[1]); }
; DI float x32_sum(float x) { const unsigned u = __builtin_bit_cast(unsigned, x); auto r = __builtin_amdgcn_permlane32_swap(u, u, false, false); return __builtin_bit_cast(float, (unsigned)r[0]) + __builtin_bit_cast(float, (unsigned)r[1]); }
;     __device__ __forceinline__ void operator()(const f32x4 (&acc)[2][2][4][2], const Unit& u, int wr, int wc, int fr, int fq) const {
;     ...
;                     const int r = row0 + ai * HALF + m * 16;
;                     const float rs = __builtin_amdgcn_rsqf((float)ss[r] * (1.0f / 1048576.0f) * (1.0f / 1024.0f) + EPS);
;                     f32x4 v[2][2]; float sq = 0.f;
; #pragma unroll
;                     for (int bj = 0; bj < 2; ++bj)
; #pragma unroll
;                         for (int n = 0; n < 2; ++n) { v[bj][n] = acc[ai][bj][m][n] * rs; sq += (v[bj][n][0] * v[bj][n][0] + v[bj][n][1] * v[bj][n][1]) + (v[bj][n][2] * v[bj][n][2] + v[bj][n][3] * v[bj][n][3]); }
;                     sq = x16_sum(sq); sq = x32_sum(sq);
;                     const float r2 = (sec < 2) ? qsc * __builtin_amdgcn_rsqf(sq * (1.0f / 64.0f) + EPS) : 1.0f;
;                     const int bl = r >> 13, t = r & 8191; const int pr = (bl << 13) + ((t & ((1 << dsh) - 1)) << (13 - dsh)) + (t >> dsh);
;                     bf16_t* rowp = O + (size_t)blk * SEC + (size_t)pr * 1024 + cin;
; #pragma unroll
;                     for (int bj = 0; bj < 2; ++bj) { const f32x4 v0 = v[bj][0] * gn[bj][0] * r2, v1 = v[bj][1] * gn[bj][1] * r2;
;                         u32x4 w; w.x = cvt_pk_bf16(v0[0], v0[1]); w.y = cvt_pk_bf16(v0[2], v0[3]); w.z = cvt_pk_bf16(v1[0], v1[1]); w.w = cvt_pk_bf16(v1[2], v1[3]);
;                         *(u32x4*)(rowp + bj * 32) = w; }
	v_pk_mul_f32 v[114:115], v[92:93], v[114:115]
	v_pk_mul_f32 v[110:111], v[94:95], v[110:111]
	v_pk_mul_f32 v[108:109], v[88:89], v[108:109]
	v_pk_mul_f32 v[106:107], v[90:91], v[106:107]
	v_lshl_add_u64 v[116:117], v[116:117], 0, v[112:113]
	v_pk_mul_f32 v[110:111], v[110:111], v[96:97] op_sel_hi:[1,0]
	v_pk_mul_f32 v[114:115], v[114:115], v[96:97] op_sel_hi:[1,0]
	v_pk_mul_f32 v[118:119], v[106:107], v[96:97] op_sel_hi:[1,0]
	v_pk_mul_f32 v[108:109], v[108:109], v[96:97] op_sel_hi:[1,0]
	v_cvt_pk_bf16_f32 v184, v114, v115
	v_cvt_pk_bf16_f32 v185, v110, v111
	v_pk_mul_f32 v[100:101], v[80:81], v[100:101]
	v_pk_mul_f32 v[98:99], v[82:83], v[98:99]
	v_cvt_pk_bf16_f32 v186, v108, v109
	v_cvt_pk_bf16_f32 v187, v118, v119
	v_pk_mul_f32 v[104:105], v[84:85], v[104:105]
	v_pk_mul_f32 v[102:103], v[86:87], v[102:103]
	v_pk_mul_f32 v[106:107], v[98:99], v[96:97] op_sel_hi:[1,0]
	v_pk_mul_f32 v[98:99], v[100:101], v[96:97] op_sel_hi:[1,0]
	v_pk_mul_f32 v[102:103], v[102:103], v[96:97] op_sel_hi:[1,0]
	v_pk_mul_f32 v[104:105], v[104:105], v[96:97] op_sel_hi:[1,0]
	s_movk_i32 s2, 0x1fff
	v_cvt_pk_bf16_f32 v96, v104, v105
	v_cvt_pk_bf16_f32 v97, v102, v103
	v_cvt_pk_bf16_f32 v98, v98, v99
	v_cvt_pk_bf16_f32 v99, v106, v107
	v_mov_b32_dpp v180, v184 row_ror:8 row_mask:0xf bank_mask:0xf
	v_mov_b32_dpp v181, v185 row_ror:8 row_mask:0xf bank_mask:0xf
	v_mov_b32_dpp v182, v186 row_ror:8 row_mask:0xf bank_mask:0xf
	v_mov_b32_dpp v183, v187 row_ror:8 row_mask:0xf bank_mask:0xf
	v_lshl_add_u64 v[212:213], v[116:117], 0, v[218:219]
	v_lshl_add_u64 v[216:217], v[116:117], 0, v[220:221]
	v_mov_b32_dpp v184, v96 row_ror:8 row_mask:0xf bank_mask:0xc
	v_mov_b32_dpp v185, v97 row_ror:8 row_mask:0xf bank_mask:0xc
	v_mov_b32_dpp v186, v98 row_ror:8 row_mask:0xf bank_mask:0xc
	v_mov_b32_dpp v187, v99 row_ror:8 row_mask:0xf bank_mask:0xc
	v_mov_b32_e32 v214, v212
	v_mov_b32_e32 v215, v213
	v_cndmask_b32_e32 v96, v180, v96, vcc
	v_cndmask_b32_e32 v97, v181, v97, vcc
	v_cndmask_b32_e32 v98, v182, v98, vcc
	v_cndmask_b32_e32 v99, v183, v99, vcc
	v_mov_b32_dpp v212, v216 row_ror:8 row_mask:0xf bank_mask:0xc
	v_mov_b32_dpp v213, v217 row_ror:8 row_mask:0xf bank_mask:0xc
	v_mov_b32_dpp v214, v216 row_ror:8 row_mask:0xf bank_mask:0x3
	v_mov_b32_dpp v215, v217 row_ror:8 row_mask:0xf bank_mask:0x3
	s_nop 0
	global_store_dwordx4 v[212:213], v[184:187], off
	global_store_dwordx4 v[214:215], v[96:99], off
	s_nop 1
	v_or_b32_e32 v99, 48, v160
	v_cvt_f32_u32_e32 v97, v199
	v_cvt_f32_u32_e32 v96, v198
	v_fmamk_f32 v96, v97, 0x4f800000, v96
	v_fmamk_f32 v96, v96, 0x30800000, v229
	v_rsq_f32_e32 v98, v96
	s_nop 0
	v_pk_mul_f32 v[78:79], v[78:79], v[98:99] op_sel_hi:[1,0]
	v_pk_mul_f32 v[222:223], v[78:79], v[78:79]
	v_pk_mul_f32 v[96:97], v[76:77], v[98:99] op_sel_hi:[1,0]
	v_pk_fma_f32 v[222:223], v[96:97], v[96:97], v[222:223]
	v_pk_mul_f32 v[74:75], v[74:75], v[98:99] op_sel_hi:[1,0]
	v_pk_fma_f32 v[222:223], v[74:75], v[74:75], v[222:223]
	v_pk_mul_f32 v[76:77], v[72:73], v[98:99] op_sel_hi:[1,0]
	v_pk_fma_f32 v[222:223], v[76:77], v[76:77], v[222:223]
	v_pk_mul_f32 v[70:71], v[70:71], v[98:99] op_sel_hi:[1,0]
	v_pk_fma_f32 v[222:223], v[70:71], v[70:71], v[222:223]
	v_pk_mul_f32 v[72:73], v[68:69], v[98:99] op_sel_hi:[1,0]
	v_pk_fma_f32 v[222:223], v[72:73], v[72:73], v[222:223]
	v_pk_mul_f32 v[66:67], v[66:67], v[98:99] op_sel_hi:[1,0]
	v_pk_fma_f32 v[222:223], v[66:67], v[66:67], v[222:223]
	v_pk_mul_f32 v[68:69], v[64:65], v[98:99] op_sel_hi:[1,0]
	v_pk_fma_f32 v[222:223], v[68:69], v[68:69], v[222:223]
	v_add_f32_e32 v64, v222, v223
	v_mov_b32_e32 v65, v64
	s_nop 1
	v_permlane16_swap_b32_e32 v64, v65
	v_add_f32_e32 v64, v64, v65
	v_mov_b32_e32 v65, v64
	s_nop 1
	v_permlane32_swap_b32_e32 v64, v65
	v_add_f32_e32 v64, v64, v65
	v_fmamk_f32 v64, v64, 0x3c800000, v229
	v_bitop3_b32 v65, v160, s2, 48 bitop3:0xc8
	v_rsq_f32_e32 v64, v64
	v_lshlrev_b32_e32 v98, s42, v99
	v_lshrrev_b32_e32 v65, s34, v65
	v_and_b32_e32 v98, 0x1ffe, v98
	v_or_b32_e32 v65, s43, v65
	v_add_u32_e32 v98, v65, v98
	v_ashrrev_i32_e32 v99, 31, v98
	v_mul_f32_e32 v64, v171, v64
	v_lshlrev_b64 v[98:99], 11, v[98:99]
	v_cndmask_b32_e64 v64, 1.0, v64, s[40:41]
	v_lshl_add_u64 v[98:99], s[0:1], 0, v[98:99]
	v_pk_mul_f32 v[96:97], v[92:93], v[96:97]
	v_pk_mul_f32 v[78:79], v[94:95], v[78:79]
	v_pk_mul_f32 v[76:77], v[88:89], v[76:77]
	v_pk_mul_f32 v[74:75], v[90:91], v[74:75]
	v_lshl_add_u64 v[98:99], v[98:99], 0, v[112:113]
	v_pk_mul_f32 v[78:79], v[78:79], v[64:65] op_sel_hi:[1,0]
	v_pk_mul_f32 v[96:97], v[96:97], v[64:65] op_sel_hi:[1,0]
	v_pk_mul_f32 v[100:101], v[74:75], v[64:65] op_sel_hi:[1,0]
	v_pk_mul_f32 v[76:77], v[76:77], v[64:65] op_sel_hi:[1,0]
	v_cvt_pk_bf16_f32 v184, v96, v97
	v_cvt_pk_bf16_f32 v185, v78, v79
	v_pk_mul_f32 v[68:69], v[80:81], v[68:69]
	v_pk_mul_f32 v[66:67], v[82:83], v[66:67]
	v_cvt_pk_bf16_f32 v186, v76, v77
	v_cvt_pk_bf16_f32 v187, v100, v101
	v_pk_mul_f32 v[72:73], v[84:85], v[72:73]
	v_pk_mul_f32 v[70:71], v[86:87], v[70:71]
	v_pk_mul_f32 v[74:75], v[66:67], v[64:65] op_sel_hi:[1,0]
	v_pk_mul_f32 v[66:67], v[68:69], v[64:65] op_sel_hi:[1,0]
	v_pk_mul_f32 v[70:71], v[70:71], v[64:65] op_sel_hi:[1,0]
	v_pk_mul_f32 v[72:73], v[72:73], v[64:65] op_sel_hi:[1,0]
	s_nop 0
	v_cvt_pk_bf16_f32 v64, v72, v73
	v_cvt_pk_bf16_f32 v65, v70, v71
	v_cvt_pk_bf16_f32 v66, v66, v67
	v_cvt_pk_bf16_f32 v67, v74, v75
	v_mov_b32_dpp v180, v184 row_ror:8 row_mask:0xf bank_mask:0xf
	v_mov_b32_dpp v181, v185 row_ror:8 row_mask:0xf bank_mask:0xf
	v_mov_b32_dpp v182, v186 row_ror:8 row_mask:0xf bank_mask:0xf
	v_mov_b32_dpp v183, v187 row_ror:8 row_mask:0xf bank_mask:0xf
	v_lshl_add_u64 v[212:213], v[98:99], 0, v[218:219]
; __device__ __forceinline__ unsigned cvt_pk_bf16(float lo, float hi) { unsigned r; asm volatile("v_cvt_pk_bf16_f32 %0, %1, %2" : "=v"(r) : "v"(lo), "v"(hi)); return r; }
; DI float x16_sum(float x) { const unsigned u = __builtin_bit_cast(unsigned, x); auto r = __builtin_amdgcn_permlane16_swap(u, u, false, false); return __builtin_bit_cast(float, (unsigned)r[0]) + __builtin_bit_cast(float, (unsigned)r[1]); }
; DI float x32_sum(float x) { const unsigned u = __builtin_bit_cast(unsigned, x); auto r = __builtin_amdgcn_permlane32_swap(u, u, false, false); return __builtin_bit_cast(float, (unsigned)r[0]) + __builtin_bit_cast(float, (unsigned)r[1]); }
;     __device__ __forceinline__ void operator()(const f32x4 (&acc)[2][2][4][2], const Unit& u, int wr, int wc, int fr, int fq) const {
;     ...
;                     const int r = row0 + ai * HALF + m * 16;
;                     const float rs = __builtin_amdgcn_rsqf((float)ss[r] * (1.0f / 1048576.0f) * (1.0f / 1024.0f) + EPS);
;                     f32x4 v[2][2]; float sq = 0.f;
; #pragma unroll
;                     for (int bj = 0; bj < 2; ++bj)
; #pragma unroll
;                         for (int n = 0; n < 2; ++n) { v[bj][n] = acc[ai][bj][m][n] * rs; sq += (v[bj][n][0] * v[bj][n][0] + v[bj][n][1] * v[bj][n][1]) + (v[bj][n][2] * v[bj][n][2] + v[bj][n][3] * v[bj][n][3]); }
;                     sq = x16_sum(sq); sq = x32_sum(sq);
;                     const float r2 = (sec < 2) ? qsc * __builtin_amdgcn_rsqf(sq * (1.0f / 64.0f) + EPS) : 1.0f;
;                     const int bl = r >> 13, t = r & 8191; const int pr = (bl << 13) + ((t & ((1 << dsh) - 1)) << (13 - dsh)) + (t >> dsh);
;                     bf16_t* rowp = O + (size_t)blk * SEC + (size_t)pr * 1024 + cin;
; #pragma unroll
;                     for (int bj = 0; bj < 2; ++bj) { const f32x4 v0 = v[bj][0] * gn[bj][0] * r2, v1 = v[bj][1] * gn[bj][1] * r2;
;                         u32x4 w; w.x = cvt_pk_bf16(v0[0], v0[1]); w.y = cvt_pk_bf16(v0[2], v0[3]); w.z = cvt_pk_bf16(v1[0], v1[1]); w.w = cvt_pk_bf16(v1[2], v1[3]);
;                         *(u32x4*)(rowp + bj * 32) = w; }
	v_lshl_add_u64 v[216:217], v[98:99], 0, v[220:221]
	v_mov_b32_dpp v184, v64 row_ror:8 row_mask:0xf bank_mask:0xc
	v_mov_b32_dpp v185, v65 row_ror:8 row_mask:0xf bank_mask:0xc
	v_mov_b32_dpp v186, v66 row_ror:8 row_mask:0xf bank_mask:0xc
	v_mov_b32_dpp v187, v67 row_ror:8 row_mask:0xf bank_mask:0xc
	v_mov_b32_e32 v214, v212
	v_mov_b32_e32 v215, v213
	v_cndmask_b32_e32 v64, v180, v64, vcc
	v_cndmask_b32_e32 v65, v181, v65, vcc
	v_cndmask_b32_e32 v66, v182, v66, vcc
	v_cndmask_b32_e32 v67, v183, v67, vcc
	v_mov_b32_dpp v212, v216 row_ror:8 row_mask:0xf bank_mask:0xc
	v_mov_b32_dpp v213, v217 row_ror:8 row_mask:0xf bank_mask:0xc
	v_mov_b32_dpp v214, v216 row_ror:8 row_mask:0xf bank_mask:0x3
	v_mov_b32_dpp v215, v217 row_ror:8 row_mask:0xf bank_mask:0x3
	s_nop 0
	global_store_dwordx4 v[212:213], v[184:187], off
	global_store_dwordx4 v[214:215], v[64:67], off
	s_nop 1
	v_add_u32_e32 v67, 0x80, v160
	v_and_b32_e32 v68, 0xffffe000, v67
	v_cvt_f32_u32_e32 v65, v201
	v_cvt_f32_u32_e32 v64, v200
	v_fmamk_f32 v64, v65, 0x4f800000, v64
	v_fmamk_f32 v64, v64, 0x30800000, v229
	v_rsq_f32_e32 v66, v64
	s_nop 0
	v_pk_mul_f32 v[62:63], v[62:63], v[66:67] op_sel_hi:[1,0]
	v_pk_mul_f32 v[222:223], v[62:63], v[62:63]
	v_pk_mul_f32 v[64:65], v[60:61], v[66:67] op_sel_hi:[1,0]
	v_pk_fma_f32 v[222:223], v[64:65], v[64:65], v[222:223]
	v_pk_mul_f32 v[58:59], v[58:59], v[66:67] op_sel_hi:[1,0]
	v_pk_fma_f32 v[222:223], v[58:59], v[58:59], v[222:223]
	v_pk_mul_f32 v[60:61], v[56:57], v[66:67] op_sel_hi:[1,0]
	v_pk_fma_f32 v[222:223], v[60:61], v[60:61], v[222:223]
	v_pk_mul_f32 v[54:55], v[54:55], v[66:67] op_sel_hi:[1,0]
	v_pk_fma_f32 v[222:223], v[54:55], v[54:55], v[222:223]
	v_pk_mul_f32 v[56:57], v[52:53], v[66:67] op_sel_hi:[1,0]
	v_pk_fma_f32 v[222:223], v[56:57], v[56:57], v[222:223]
	v_pk_mul_f32 v[50:51], v[50:51], v[66:67] op_sel_hi:[1,0]
	v_pk_fma_f32 v[222:223], v[50:51], v[50:51], v[222:223]
	v_pk_mul_f32 v[52:53], v[48:49], v[66:67] op_sel_hi:[1,0]
	v_pk_fma_f32 v[222:223], v[52:53], v[52:53], v[222:223]
	v_add_f32_e32 v48, v222, v223
	v_mov_b32_e32 v49, v48
	s_nop 1
	v_permlane16_swap_b32_e32 v48, v49
	v_add_f32_e32 v48, v48, v49
	v_mov_b32_e32 v49, v48
	s_nop 1
	v_permlane32_swap_b32_e32 v48, v49
	v_add_f32_e32 v48, v48, v49
	v_fmamk_f32 v48, v48, 0x3c800000, v229
	v_and_b32_e32 v49, 0x1fcf, v67
	v_rsq_f32_e32 v48, v48
	v_lshlrev_b32_e32 v66, s42, v67
	v_lshrrev_b32_e32 v49, s34, v49
	v_and_b32_e32 v66, 0x1ffe, v66
	v_or_b32_e32 v49, v49, v68
	v_add_u32_e32 v66, v49, v66
	v_ashrrev_i32_e32 v67, 31, v66
	v_mul_f32_e32 v48, v171, v48
	v_lshlrev_b64 v[66:67], 11, v[66:67]
	v_cndmask_b32_e64 v48, 1.0, v48, s[40:41]
	v_lshl_add_u64 v[66:67], s[0:1], 0, v[66:67]
	v_pk_mul_f32 v[64:65], v[92:93], v[64:65]
	v_pk_mul_f32 v[62:63], v[94:95], v[62:63]
	v_pk_mul_f32 v[60:61], v[88:89], v[60:61]
	v_pk_mul_f32 v[58:59], v[90:91], v[58:59]
	v_lshl_add_u64 v[66:67], v[66:67], 0, v[112:113]
	v_pk_mul_f32 v[62:63], v[62:63], v[48:49] op_sel_hi:[1,0]
	v_pk_mul_f32 v[64:65], v[64:65], v[48:49] op_sel_hi:[1,0]
	v_pk_mul_f32 v[70:71], v[58:59], v[48:49] op_sel_hi:[1,0]
	v_pk_mul_f32 v[60:61], v[60:61], v[48:49] op_sel_hi:[1,0]
	v_cvt_pk_bf16_f32 v184, v64, v65
	v_cvt_pk_bf16_f32 v185, v62, v63
	v_pk_mul_f32 v[52:53], v[80:81], v[52:53]
	v_pk_mul_f32 v[50:51], v[82:83], v[50:51]
	v_cvt_pk_bf16_f32 v186, v60, v61
	v_cvt_pk_bf16_f32 v187, v70, v71
	v_pk_mul_f32 v[56:57], v[84:85], v[56:57]
	v_pk_mul_f32 v[54:55], v[86:87], v[54:55]
	v_pk_mul_f32 v[58:59], v[50:51], v[48:49] op_sel_hi:[1,0]
	v_pk_mul_f32 v[50:51], v[52:53], v[48:49] op_sel_hi:[1,0]
	v_pk_mul_f32 v[54:55], v[54:55], v[48:49] op_sel_hi:[1,0]
	v_pk_mul_f32 v[56:57], v[56:57], v[48:49] op_sel_hi:[1,0]
	s_nop 0
	v_cvt_pk_bf16_f32 v48, v56, v57
	v_cvt_pk_bf16_f32 v49, v54, v55
	v_cvt_pk_bf16_f32 v50, v50, v51
	v_cvt_pk_bf16_f32 v51, v58, v59
	v_mov_b32_dpp v180, v184 row_ror:8 row_mask:0xf bank_mask:0xf
	v_mov_b32_dpp v181, v185 row_ror:8 row_mask:0xf bank_mask:0xf
	v_mov_b32_dpp v182, v186 row_ror:8 row_mask:0xf bank_mask:0xf
	v_mov_b32_dpp v183, v187 row_ror:8 row_mask:0xf bank_mask:0xf
	v_lshl_add_u64 v[212:213], v[66:67], 0, v[218:219]
	v_lshl_add_u64 v[216:217], v[66:67], 0, v[220:221]
	v_mov_b32_dpp v184, v48 row_ror:8 row_mask:0xf bank_mask:0xc
	v_mov_b32_dpp v185, v49 row_ror:8 row_mask:0xf bank_mask:0xc
	v_mov_b32_dpp v186, v50 row_ror:8 row_mask:0xf bank_mask:0xc
	v_mov_b32_dpp v187, v51 row_ror:8 row_mask:0xf bank_mask:0xc
	v_mov_b32_e32 v214, v212
	v_mov_b32_e32 v215, v213
	v_cndmask_b32_e32 v48, v180, v48, vcc
	v_cndmask_b32_e32 v49, v181, v49, vcc
	v_cndmask_b32_e32 v50, v182, v50, vcc
	v_cndmask_b32_e32 v51, v183, v51, vcc
	v_mov_b32_dpp v212, v216 row_ror:8 row_mask:0xf bank_mask:0xc
	v_mov_b32_dpp v213, v217 row_ror:8 row_mask:0xf bank_mask:0xc
	v_mov_b32_dpp v214, v216 row_ror:8 row_mask:0xf bank_mask:0x3
	v_mov_b32_dpp v215, v217 row_ror:8 row_mask:0xf bank_mask:0x3
	s_nop 0
	global_store_dwordx4 v[212:213], v[184:187], off
	global_store_dwordx4 v[214:215], v[48:51], off
	s_nop 1
	v_add_u32_e32 v51, 0x90, v160
	v_cvt_f32_u32_e32 v49, v203
	v_cvt_f32_u32_e32 v48, v202
	v_fmamk_f32 v48, v49, 0x4f800000, v48
	v_fmamk_f32 v48, v48, 0x30800000, v229
	v_rsq_f32_e32 v50, v48
	s_nop 0
	v_pk_mul_f32 v[46:47], v[46:47], v[50:51] op_sel_hi:[1,0]
	v_pk_mul_f32 v[222:223], v[46:47], v[46:47]
	v_pk_mul_f32 v[48:49], v[44:45], v[50:51] op_sel_hi:[1,0]
	v_pk_fma_f32 v[222:223], v[48:49], v[48:49], v[222:223]
	v_pk_mul_f32 v[42:43], v[42:43], v[50:51] op_sel_hi:[1,0]
	v_pk_fma_f32 v[222:223], v[42:43], v[42:43], v[222:223]
	v_pk_mul_f32 v[44:45], v[40:41], v[50:51] op_sel_hi:[1,0]
; __device__ __forceinline__ unsigned cvt_pk_bf16(float lo, float hi) { unsigned r; asm volatile("v_cvt_pk_bf16_f32 %0, %1, %2" : "=v"(r) : "v"(lo), "v"(hi)); return r; }
; DI float x16_sum(float x) { const unsigned u = __builtin_bit_cast(unsigned, x); auto r = __builtin_amdgcn_permlane16_swap(u, u, false, false); return __builtin_bit_cast(float, (unsigned)r[0]) + __builtin_bit_cast(float, (unsigned)r[1]); }
; DI float x32_sum(float x) { const unsigned u = __builtin_bit_cast(unsigned, x); auto r = __builtin_amdgcn_permlane32_swap(u, u, false, false); return __builtin_bit_cast(float, (unsigned)r[0]) + __builtin_bit_cast(float, (unsigned)r[1]); }
;     __device__ __forceinline__ void operator()(const f32x4 (&acc)[2][2][4][2], const Unit& u, int wr, int wc, int fr, int fq) const {
;     ...
;                     const int r = row0 + ai * HALF + m * 16;
;                     const float rs = __builtin_amdgcn_rsqf((float)ss[r] * (1.0f / 1048576.0f) * (1.0f / 1024.0f) + EPS);
;                     f32x4 v[2][2]; float sq = 0.f;
; #pragma unroll
;                     for (int bj = 0; bj < 2; ++bj)
; #pragma unroll
;                         for (int n = 0; n < 2; ++n) { v[bj][n] = acc[ai][bj][m][n] * rs; sq += (v[bj][n][0] * v[bj][n][0] + v[bj][n][1] * v[bj][n][1]) + (v[bj][n][2] * v[bj][n][2] + v[bj][n][3] * v[bj][n][3]); }
;                     sq = x16_sum(sq); sq = x32_sum(sq);
;                     const float r2 = (sec < 2) ? qsc * __builtin_amdgcn_rsqf(sq * (1.0f / 64.0f) + EPS) : 1.0f;
;                     const int bl = r >> 13, t = r & 8191; const int pr = (bl << 13) + ((t & ((1 << dsh) - 1)) << (13 - dsh)) + (t >> dsh);
;                     bf16_t* rowp = O + (size_t)blk * SEC + (size_t)pr * 1024 + cin;
; #pragma unroll
;                     for (int bj = 0; bj < 2; ++bj) { const f32x4 v0 = v[bj][0] * gn[bj][0] * r2, v1 = v[bj][1] * gn[bj][1] * r2;
;                         u32x4 w; w.x = cvt_pk_bf16(v0[0], v0[1]); w.y = cvt_pk_bf16(v0[2], v0[3]); w.z = cvt_pk_bf16(v1[0], v1[1]); w.w = cvt_pk_bf16(v1[2], v1[3]);
;                         *(u32x4*)(rowp + bj * 32) = w; }
	v_pk_fma_f32 v[222:223], v[44:45], v[44:45], v[222:223]
	v_pk_mul_f32 v[38:39], v[38:39], v[50:51] op_sel_hi:[1,0]
	v_pk_fma_f32 v[222:223], v[38:39], v[38:39], v[222:223]
	v_pk_mul_f32 v[40:41], v[36:37], v[50:51] op_sel_hi:[1,0]
	v_pk_fma_f32 v[222:223], v[40:41], v[40:41], v[222:223]
	v_pk_mul_f32 v[34:35], v[34:35], v[50:51] op_sel_hi:[1,0]
	v_pk_fma_f32 v[222:223], v[34:35], v[34:35], v[222:223]
	v_pk_mul_f32 v[36:37], v[32:33], v[50:51] op_sel_hi:[1,0]
	v_pk_fma_f32 v[222:223], v[36:37], v[36:37], v[222:223]
	v_add_f32_e32 v32, v222, v223
	v_mov_b32_e32 v33, v32
	s_nop 1
	v_permlane16_swap_b32_e32 v32, v33
	v_add_f32_e32 v32, v32, v33
	v_mov_b32_e32 v33, v32
	s_nop 1
	v_permlane32_swap_b32_e32 v32, v33
	v_add_f32_e32 v32, v32, v33
	v_fmamk_f32 v32, v32, 0x3c800000, v229
	v_and_b32_e32 v33, 0x1fdf, v51
	v_rsq_f32_e32 v32, v32
	v_lshlrev_b32_e32 v50, s42, v51
	v_lshrrev_b32_e32 v33, s34, v33
	v_and_b32_e32 v50, 0x1ffe, v50
	v_or_b32_e32 v33, v33, v68
	v_add_u32_e32 v50, v33, v50
	v_ashrrev_i32_e32 v51, 31, v50
	v_mul_f32_e32 v32, v171, v32
	v_lshlrev_b64 v[50:51], 11, v[50:51]
	v_cndmask_b32_e64 v32, 1.0, v32, s[40:41]
	v_lshl_add_u64 v[50:51], s[0:1], 0, v[50:51]
	v_pk_mul_f32 v[48:49], v[92:93], v[48:49]
	v_pk_mul_f32 v[46:47], v[94:95], v[46:47]
	v_pk_mul_f32 v[44:45], v[88:89], v[44:45]
	v_pk_mul_f32 v[42:43], v[90:91], v[42:43]
	v_lshl_add_u64 v[50:51], v[50:51], 0, v[112:113]
	v_pk_mul_f32 v[46:47], v[46:47], v[32:33] op_sel_hi:[1,0]
	v_pk_mul_f32 v[48:49], v[48:49], v[32:33] op_sel_hi:[1,0]
	v_pk_mul_f32 v[52:53], v[42:43], v[32:33] op_sel_hi:[1,0]
	v_pk_mul_f32 v[44:45], v[44:45], v[32:33] op_sel_hi:[1,0]
	v_cvt_pk_bf16_f32 v184, v48, v49
	v_cvt_pk_bf16_f32 v185, v46, v47
	v_pk_mul_f32 v[36:37], v[80:81], v[36:37]
	v_pk_mul_f32 v[34:35], v[82:83], v[34:35]
	v_cvt_pk_bf16_f32 v186, v44, v45
	v_cvt_pk_bf16_f32 v187, v52, v53
	v_pk_mul_f32 v[40:41], v[84:85], v[40:41]
	v_pk_mul_f32 v[38:39], v[86:87], v[38:39]
	v_pk_mul_f32 v[42:43], v[34:35], v[32:33] op_sel_hi:[1,0]
	v_pk_mul_f32 v[34:35], v[36:37], v[32:33] op_sel_hi:[1,0]
	v_pk_mul_f32 v[38:39], v[38:39], v[32:33] op_sel_hi:[1,0]
	v_pk_mul_f32 v[40:41], v[40:41], v[32:33] op_sel_hi:[1,0]
	s_nop 0
	v_cvt_pk_bf16_f32 v32, v40, v41
	v_cvt_pk_bf16_f32 v33, v38, v39
	v_cvt_pk_bf16_f32 v34, v34, v35
	v_cvt_pk_bf16_f32 v35, v42, v43
	v_mov_b32_dpp v180, v184 row_ror:8 row_mask:0xf bank_mask:0xf
	v_mov_b32_dpp v181, v185 row_ror:8 row_mask:0xf bank_mask:0xf
	v_mov_b32_dpp v182, v186 row_ror:8 row_mask:0xf bank_mask:0xf
	v_mov_b32_dpp v183, v187 row_ror:8 row_mask:0xf bank_mask:0xf
	v_lshl_add_u64 v[212:213], v[50:51], 0, v[218:219]
	v_lshl_add_u64 v[216:217], v[50:51], 0, v[220:221]
	v_mov_b32_dpp v184, v32 row_ror:8 row_mask:0xf bank_mask:0xc
	v_mov_b32_dpp v185, v33 row_ror:8 row_mask:0xf bank_mask:0xc
	v_mov_b32_dpp v186, v34 row_ror:8 row_mask:0xf bank_mask:0xc
	v_mov_b32_dpp v187, v35 row_ror:8 row_mask:0xf bank_mask:0xc
	v_mov_b32_e32 v214, v212
	v_mov_b32_e32 v215, v213
	v_cndmask_b32_e32 v32, v180, v32, vcc
	v_cndmask_b32_e32 v33, v181, v33, vcc
	v_cndmask_b32_e32 v34, v182, v34, vcc
	v_cndmask_b32_e32 v35, v183, v35, vcc
	v_mov_b32_dpp v212, v216 row_ror:8 row_mask:0xf bank_mask:0xc
	v_mov_b32_dpp v213, v217 row_ror:8 row_mask:0xf bank_mask:0xc
	v_mov_b32_dpp v214, v216 row_ror:8 row_mask:0xf bank_mask:0x3
	v_mov_b32_dpp v215, v217 row_ror:8 row_mask:0xf bank_mask:0x3
	s_nop 0
	global_store_dwordx4 v[212:213], v[184:187], off
	global_store_dwordx4 v[214:215], v[32:35], off
	s_nop 1
	v_add_u32_e32 v35, 0xa0, v160
	v_cvt_f32_u32_e32 v33, v205
	v_cvt_f32_u32_e32 v32, v204
	v_fmamk_f32 v32, v33, 0x4f800000, v32
	v_fmamk_f32 v32, v32, 0x30800000, v229
	v_rsq_f32_e32 v34, v32
	s_nop 0
	v_pk_mul_f32 v[30:31], v[30:31], v[34:35] op_sel_hi:[1,0]
	v_pk_mul_f32 v[222:223], v[30:31], v[30:31]
	v_pk_mul_f32 v[32:33], v[28:29], v[34:35] op_sel_hi:[1,0]
	v_pk_fma_f32 v[222:223], v[32:33], v[32:33], v[222:223]
	v_pk_mul_f32 v[26:27], v[26:27], v[34:35] op_sel_hi:[1,0]
	v_pk_fma_f32 v[222:223], v[26:27], v[26:27], v[222:223]
	v_pk_mul_f32 v[28:29], v[24:25], v[34:35] op_sel_hi:[1,0]
	v_pk_fma_f32 v[222:223], v[28:29], v[28:29], v[222:223]
	v_pk_mul_f32 v[22:23], v[22:23], v[34:35] op_sel_hi:[1,0]
	v_pk_fma_f32 v[222:223], v[22:23], v[22:23], v[222:223]
	v_pk_mul_f32 v[24:25], v[20:21], v[34:35] op_sel_hi:[1,0]
	v_pk_fma_f32 v[222:223], v[24:25], v[24:25], v[222:223]
	v_pk_mul_f32 v[18:19], v[18:19], v[34:35] op_sel_hi:[1,0]
	v_pk_fma_f32 v[222:223], v[18:19], v[18:19], v[222:223]
	v_pk_mul_f32 v[20:21], v[16:17], v[34:35] op_sel_hi:[1,0]
	v_pk_fma_f32 v[222:223], v[20:21], v[20:21], v[222:223]
	v_add_f32_e32 v16, v222, v223
	v_mov_b32_e32 v17, v16
	s_nop 1
	v_permlane16_swap_b32_e32 v16, v17
	v_add_f32_e32 v16, v16, v17
	v_mov_b32_e32 v17, v16
	s_nop 1
	v_permlane32_swap_b32_e32 v16, v17
	v_add_f32_e32 v16, v16, v17
	v_fmamk_f32 v16, v16, 0x3c800000, v229
	v_and_b32_e32 v17, 0x1fef, v35
	v_rsq_f32_e32 v16, v16
	v_lshlrev_b32_e32 v34, s42, v35
	v_lshrrev_b32_e32 v17, s34, v17
	v_and_b32_e32 v34, 0x1ffe, v34
	v_or_b32_e32 v17, v17, v68
	v_add_u32_e32 v34, v17, v34
	v_ashrrev_i32_e32 v35, 31, v34
	v_mul_f32_e32 v16, v171, v16
	v_lshlrev_b64 v[34:35], 11, v[34:35]
	v_cndmask_b32_e64 v16, 1.0, v16, s[40:41]
	v_lshl_add_u64 v[34:35], s[0:1], 0, v[34:35]
	v_pk_mul_f32 v[32:33], v[92:93], v[32:33]
	v_pk_mul_f32 v[30:31], v[94:95], v[30:31]
	v_pk_mul_f32 v[28:29], v[88:89], v[28:29]
	v_pk_mul_f32 v[26:27], v[90:91], v[26:27]
	v_lshl_add_u64 v[34:35], v[34:35], 0, v[112:113]
	v_pk_mul_f32 v[30:31], v[30:31], v[16:17] op_sel_hi:[1,0]
	v_pk_mul_f32 v[32:33], v[32:33], v[16:17] op_sel_hi:[1,0]
; __device__ __forceinline__ unsigned cvt_pk_bf16(float lo, float hi) { unsigned r; asm volatile("v_cvt_pk_bf16_f32 %0, %1, %2" : "=v"(r) : "v"(lo), "v"(hi)); return r; }
; DI float x16_sum(float x) { const unsigned u = __builtin_bit_cast(unsigned, x); auto r = __builtin_amdgcn_permlane16_swap(u, u, false, false); return __builtin_bit_cast(float, (unsigned)r[0]) + __builtin_bit_cast(float, (unsigned)r[1]); }
; DI float x32_sum(float x) { const unsigned u = __builtin_bit_cast(unsigned, x); auto r = __builtin_amdgcn_permlane32_swap(u, u, false, false); return __builtin_bit_cast(float, (unsigned)r[0]) + __builtin_bit_cast(float, (unsigned)r[1]); }
; template <class Epi, class Sched, bool ALIGN_EPI = false, bool SP2 = false>
; __device__ __forceinline__ void gemm_phase(PG8_LAS unsigned char* lds, const Gemm g, const Sched& S, const Epi& E) {
;     ...
;         if (!has_next) break;
;     __device__ __forceinline__ void operator()(const f32x4 (&acc)[2][2][4][2], const Unit& u, int wr, int wc, int fr, int fq) const {
;     ...
;                     const int r = row0 + ai * HALF + m * 16;
;                     const float rs = __builtin_amdgcn_rsqf((float)ss[r] * (1.0f / 1048576.0f) * (1.0f / 1024.0f) + EPS);
;                     f32x4 v[2][2]; float sq = 0.f;
; #pragma unroll
;                     for (int bj = 0; bj < 2; ++bj)
; #pragma unroll
;                         for (int n = 0; n < 2; ++n) { v[bj][n] = acc[ai][bj][m][n] * rs; sq += (v[bj][n][0] * v[bj][n][0] + v[bj][n][1] * v[bj][n][1]) + (v[bj][n][2] * v[bj][n][2] + v[bj][n][3] * v[bj][n][3]); }
;                     sq = x16_sum(sq); sq = x32_sum(sq);
;                     const float r2 = (sec < 2) ? qsc * __builtin_amdgcn_rsqf(sq * (1.0f / 64.0f) + EPS) : 1.0f;
;                     const int bl = r >> 13, t = r & 8191; const int pr = (bl << 13) + ((t & ((1 << dsh) - 1)) << (13 - dsh)) + (t >> dsh);
;                     bf16_t* rowp = O + (size_t)blk * SEC + (size_t)pr * 1024 + cin;
; #pragma unroll
;                     for (int bj = 0; bj < 2; ++bj) { const f32x4 v0 = v[bj][0] * gn[bj][0] * r2, v1 = v[bj][1] * gn[bj][1] * r2;
;                         u32x4 w; w.x = cvt_pk_bf16(v0[0], v0[1]); w.y = cvt_pk_bf16(v0[2], v0[3]); w.z = cvt_pk_bf16(v1[0], v1[1]); w.w = cvt_pk_bf16(v1[2], v1[3]);
;                         *(u32x4*)(rowp + bj * 32) = w; }
	v_pk_mul_f32 v[36:37], v[26:27], v[16:17] op_sel_hi:[1,0]
	v_pk_mul_f32 v[28:29], v[28:29], v[16:17] op_sel_hi:[1,0]
	v_cvt_pk_bf16_f32 v184, v32, v33
	v_cvt_pk_bf16_f32 v185, v30, v31
	v_pk_mul_f32 v[20:21], v[80:81], v[20:21]
	v_pk_mul_f32 v[18:19], v[82:83], v[18:19]
	v_cvt_pk_bf16_f32 v186, v28, v29
	v_cvt_pk_bf16_f32 v187, v36, v37
	v_pk_mul_f32 v[24:25], v[84:85], v[24:25]
	v_pk_mul_f32 v[22:23], v[86:87], v[22:23]
	v_pk_mul_f32 v[26:27], v[18:19], v[16:17] op_sel_hi:[1,0]
	v_pk_mul_f32 v[18:19], v[20:21], v[16:17] op_sel_hi:[1,0]
	v_pk_mul_f32 v[22:23], v[22:23], v[16:17] op_sel_hi:[1,0]
	v_pk_mul_f32 v[24:25], v[24:25], v[16:17] op_sel_hi:[1,0]
	s_nop 0
	v_cvt_pk_bf16_f32 v16, v24, v25
	v_cvt_pk_bf16_f32 v17, v22, v23
	v_cvt_pk_bf16_f32 v18, v18, v19
	v_cvt_pk_bf16_f32 v19, v26, v27
	v_mov_b32_dpp v180, v184 row_ror:8 row_mask:0xf bank_mask:0xf
	v_mov_b32_dpp v181, v185 row_ror:8 row_mask:0xf bank_mask:0xf
	v_mov_b32_dpp v182, v186 row_ror:8 row_mask:0xf bank_mask:0xf
	v_mov_b32_dpp v183, v187 row_ror:8 row_mask:0xf bank_mask:0xf
	v_lshl_add_u64 v[212:213], v[34:35], 0, v[218:219]
	v_lshl_add_u64 v[216:217], v[34:35], 0, v[220:221]
	v_mov_b32_dpp v184, v16 row_ror:8 row_mask:0xf bank_mask:0xc
	v_mov_b32_dpp v185, v17 row_ror:8 row_mask:0xf bank_mask:0xc
	v_mov_b32_dpp v186, v18 row_ror:8 row_mask:0xf bank_mask:0xc
	v_mov_b32_dpp v187, v19 row_ror:8 row_mask:0xf bank_mask:0xc
	v_mov_b32_e32 v214, v212
	v_mov_b32_e32 v215, v213
	v_cndmask_b32_e32 v16, v180, v16, vcc
	v_cndmask_b32_e32 v17, v181, v17, vcc
	v_cndmask_b32_e32 v18, v182, v18, vcc
	v_cndmask_b32_e32 v19, v183, v19, vcc
	v_mov_b32_dpp v212, v216 row_ror:8 row_mask:0xf bank_mask:0xc
	v_mov_b32_dpp v213, v217 row_ror:8 row_mask:0xf bank_mask:0xc
	v_mov_b32_dpp v214, v216 row_ror:8 row_mask:0xf bank_mask:0x3
	v_mov_b32_dpp v215, v217 row_ror:8 row_mask:0xf bank_mask:0x3
	s_nop 0
	global_store_dwordx4 v[212:213], v[184:187], off
	global_store_dwordx4 v[214:215], v[16:19], off
	s_nop 1
	v_add_u32_e32 v19, 0xb0, v160
	v_cvt_f32_u32_e32 v17, v207
	v_cvt_f32_u32_e32 v16, v206
	v_fmamk_f32 v16, v17, 0x4f800000, v16
	v_fmamk_f32 v16, v16, 0x30800000, v229
	v_rsq_f32_e32 v18, v16
	s_nop 0
	v_pk_mul_f32 v[14:15], v[14:15], v[18:19] op_sel_hi:[1,0]
	v_pk_mul_f32 v[222:223], v[14:15], v[14:15]
	v_pk_mul_f32 v[16:17], v[12:13], v[18:19] op_sel_hi:[1,0]
	v_pk_fma_f32 v[222:223], v[16:17], v[16:17], v[222:223]
	v_pk_mul_f32 v[10:11], v[10:11], v[18:19] op_sel_hi:[1,0]
	v_pk_fma_f32 v[222:223], v[10:11], v[10:11], v[222:223]
	v_pk_mul_f32 v[12:13], v[8:9], v[18:19] op_sel_hi:[1,0]
	v_pk_fma_f32 v[222:223], v[12:13], v[12:13], v[222:223]
	v_pk_mul_f32 v[6:7], v[6:7], v[18:19] op_sel_hi:[1,0]
	v_pk_fma_f32 v[222:223], v[6:7], v[6:7], v[222:223]
	v_pk_mul_f32 v[8:9], v[4:5], v[18:19] op_sel_hi:[1,0]
	v_pk_fma_f32 v[222:223], v[8:9], v[8:9], v[222:223]
	v_pk_mul_f32 v[2:3], v[2:3], v[18:19] op_sel_hi:[1,0]
	v_pk_fma_f32 v[222:223], v[2:3], v[2:3], v[222:223]
	v_pk_mul_f32 v[4:5], v[0:1], v[18:19] op_sel_hi:[1,0]
	v_pk_fma_f32 v[222:223], v[4:5], v[4:5], v[222:223]
	v_add_f32_e32 v0, v222, v223
	v_mov_b32_e32 v1, v0
	s_nop 1
	v_permlane16_swap_b32_e32 v0, v1
	v_add_f32_e32 v0, v0, v1
	v_mov_b32_e32 v1, v0
	s_nop 1
	v_permlane32_swap_b32_e32 v0, v1
	v_add_f32_e32 v0, v0, v1
	v_fmamk_f32 v0, v0, 0x3c800000, v229
	v_and_b32_e32 v1, 0x1fff, v19
	v_rsq_f32_e32 v0, v0
	v_lshlrev_b32_e32 v18, s42, v19
	v_lshrrev_b32_e32 v1, s34, v1
	v_and_b32_e32 v18, 0x1ffe, v18
	v_or_b32_e32 v1, v1, v68
	v_add_u32_e32 v18, v1, v18
	v_ashrrev_i32_e32 v19, 31, v18
	v_mul_f32_e32 v0, v171, v0
	v_lshlrev_b64 v[18:19], 11, v[18:19]
	v_cndmask_b32_e64 v0, 1.0, v0, s[40:41]
	v_lshl_add_u64 v[18:19], s[0:1], 0, v[18:19]
	v_pk_mul_f32 v[16:17], v[92:93], v[16:17]
	v_pk_mul_f32 v[14:15], v[94:95], v[14:15]
	v_pk_mul_f32 v[12:13], v[88:89], v[12:13]
	v_pk_mul_f32 v[10:11], v[90:91], v[10:11]
	v_lshl_add_u64 v[18:19], v[18:19], 0, v[112:113]
	v_pk_mul_f32 v[14:15], v[14:15], v[0:1] op_sel_hi:[1,0]
	v_pk_mul_f32 v[16:17], v[16:17], v[0:1] op_sel_hi:[1,0]
	v_pk_mul_f32 v[20:21], v[10:11], v[0:1] op_sel_hi:[1,0]
	v_pk_mul_f32 v[12:13], v[12:13], v[0:1] op_sel_hi:[1,0]
	v_cvt_pk_bf16_f32 v184, v16, v17
	v_cvt_pk_bf16_f32 v185, v14, v15
	v_pk_mul_f32 v[4:5], v[80:81], v[4:5]
	v_pk_mul_f32 v[2:3], v[82:83], v[2:3]
	v_cvt_pk_bf16_f32 v186, v12, v13
	v_cvt_pk_bf16_f32 v187, v20, v21
	v_pk_mul_f32 v[8:9], v[84:85], v[8:9]
	v_pk_mul_f32 v[6:7], v[86:87], v[6:7]
	v_pk_mul_f32 v[10:11], v[2:3], v[0:1] op_sel_hi:[1,0]
	v_pk_mul_f32 v[2:3], v[4:5], v[0:1] op_sel_hi:[1,0]
	v_pk_mul_f32 v[6:7], v[6:7], v[0:1] op_sel_hi:[1,0]
	v_pk_mul_f32 v[8:9], v[8:9], v[0:1] op_sel_hi:[1,0]
	s_nop 0
	v_cvt_pk_bf16_f32 v0, v8, v9
	v_cvt_pk_bf16_f32 v1, v6, v7
	v_cvt_pk_bf16_f32 v2, v2, v3
	v_cvt_pk_bf16_f32 v3, v10, v11
	v_mov_b32_dpp v180, v184 row_ror:8 row_mask:0xf bank_mask:0xf
	v_mov_b32_dpp v181, v185 row_ror:8 row_mask:0xf bank_mask:0xf
	v_mov_b32_dpp v182, v186 row_ror:8 row_mask:0xf bank_mask:0xf
	v_mov_b32_dpp v183, v187 row_ror:8 row_mask:0xf bank_mask:0xf
	v_lshl_add_u64 v[212:213], v[18:19], 0, v[218:219]
	v_lshl_add_u64 v[216:217], v[18:19], 0, v[220:221]
	v_mov_b32_dpp v184, v0 row_ror:8 row_mask:0xf bank_mask:0xc
	v_mov_b32_dpp v185, v1 row_ror:8 row_mask:0xf bank_mask:0xc
	v_mov_b32_dpp v186, v2 row_ror:8 row_mask:0xf bank_mask:0xc
	v_mov_b32_dpp v187, v3 row_ror:8 row_mask:0xf bank_mask:0xc
	v_mov_b32_e32 v214, v212
	v_mov_b32_e32 v215, v213
	v_cndmask_b32_e32 v0, v180, v0, vcc
	v_cndmask_b32_e32 v1, v181, v1, vcc
	v_cndmask_b32_e32 v2, v182, v2, vcc
	v_cndmask_b32_e32 v3, v183, v3, vcc
	v_mov_b32_dpp v212, v216 row_ror:8 row_mask:0xf bank_mask:0xc
	v_mov_b32_dpp v213, v217 row_ror:8 row_mask:0xf bank_mask:0xc
	v_mov_b32_dpp v214, v216 row_ror:8 row_mask:0xf bank_mask:0x3
	v_mov_b32_dpp v215, v217 row_ror:8 row_mask:0xf bank_mask:0x3
	s_nop 0
	global_store_dwordx4 v[212:213], v[184:187], off
	global_store_dwordx4 v[214:215], v[0:3], off
	s_andn2_b64 vcc, exec, s[38:39]
	s_mov_b64 s[0:1], -1
	s_cbranch_vccnz .LBB0_350
